# LRUC: XR tiles fetched row-contiguously (8 full lines per load instead of 32 rows x 32 B) and re-laid through a wave-private LDS tile (pitch 144 B) into the MFMA A layout
# speedup vs baseline: 1.0019x; 1.0019x over previous
; template <int DIR>
; __device__ __forceinline__ void lru_dir(const bf16_t* XR, const bf16_t* GATE, bf16_t* YP, u32x4* HSF, const bf16_t* bdw_dir, float bias_r, float bias_i, float sp,
;                                         int b, int n2, int lane, int wave, LAS float* xl) {
;     const int e = lane & 31, hh = lane >> 5, n = n2 >> 1, half = n2 & 1;
;     const int tau = 16 * ((e >> 2) & 1) + (e & 3) + 4 * (e >> 3);
;     bf16x8 Br[4], Bi[4];
;     const bf16_t* wrp = bdw_dir + (size_t)n * 4096 + (half * 32 + e) * 64 + 8 * hh;
;     const bf16_t* wip = wrp + 16 * 4096;
; #pragma unroll
;     for (int kk = 0; kk < 4; ++kk) { Br[kk] = *(const bf16x8*)(wrp + 16 * kk); Bi[kk] = *(const bf16x8*)(wip + 16 * kk); }
;     bf16x8 I0, I1;
; #pragma unroll
;     for (int jj = 0; jj < 8; ++jj) { I0[jj] = (8 * hh + jj == e) ? (short)0x3F80 : (short)0; I1[jj] = (16 + 8 * hh + jj == e) ? (short)0x3F80 : (short)0; }
;     const bool first = (hh == DIR);
;     const int chcol = n * 64 + half * 32;
;     const float spm = -8.0f * 1.4426950408889634f * sp;
; __device__ __forceinline__ void lru_block_phase(const bf16_t* XR, const bf16_t* GATE, bf16_t* YP, u32x4* HSF, const bf16_t* bdw_j, const float* ga_b, const float* gx_b, const float* lam,
;                                                 LAS unsigned char* lds, int lane, int wave, int G) {
;     ...
;         const int b = item >> 5, n2 = item & 31, ch = n2 * 32 + (lane & 31);
;         { const float bias_r = ga_b[ch], bias_i = gx_b[ch], sp = log1pf(__expf(-lam[ch]));
.LBB0_19:
	s_and_b32 s2, s12, 31
	v_lshl_or_b32 v111, s2, 5, v172
	v_lshlrev_b32_e32 v0, 2, v111
	global_load_dword v114, v0, s[66:67]
	global_load_dword v116, v0, s[68:69]
	s_nop 0
	global_load_dword v0, v0, s[70:71]
	s_mov_b32 s3, 0x3f2aaaab
	s_ashr_i32 s34, s12, 5
	s_and_b32 s35, s12, 1
	v_lshl_or_b32 v48, s35, 12, v179
	v_mov_b32_e32 v109, v49
	s_mov_b32 s18, 0
	v_mov_b32_e32 v101, 0
	s_mov_b32 s38, s22
	s_mov_b32 s39, 0
	s_waitcnt vmcnt(0)
	v_mov_b32_e32 v115, v114
	s_waitcnt vmcnt(1)
	v_mov_b32_e32 v117, v116
	s_waitcnt vmcnt(0)
	v_mul_f32_e32 v0, 0xbfb8aa3b, v0
	v_exp_f32_e32 v14, v0
	s_nop 0
	v_add_f32_e32 v2, 1.0, v14
	v_add_f32_e32 v0, -1.0, v2
	v_sub_f32_e32 v1, v0, v2
	v_add_f32_e32 v1, 1.0, v1
	v_sub_f32_e32 v0, v14, v0
	v_add_f32_e32 v3, v0, v1
	v_frexp_mant_f32_e32 v0, v2
	v_cmp_gt_f32_e32 vcc, s3, v0
	v_cvt_f64_f32_e32 v[0:1], v2
	v_frexp_exp_i32_f64_e32 v0, v[0:1]
	v_subbrev_co_u32_e32 v8, vcc, 0, v0, vcc
	v_sub_u32_e32 v0, 0, v8
	v_ldexp_f32 v1, v2, v0
	v_add_f32_e32 v2, -1.0, v1
	v_add_f32_e32 v4, 1.0, v1
	v_ldexp_f32 v0, v3, v0
	v_add_f32_e32 v3, 1.0, v2
	v_add_f32_e32 v5, -1.0, v4
	v_sub_f32_e32 v3, v1, v3
	v_sub_f32_e32 v1, v1, v5
	v_add_f32_e32 v3, v0, v3
	v_add_f32_e32 v0, v0, v1
	v_add_f32_e32 v9, v4, v0
	v_rcp_f32_e32 v11, v9
	v_sub_f32_e32 v1, v9, v4
	v_sub_f32_e32 v10, v0, v1
	v_add_f32_e32 v1, v2, v3
	v_mul_f32_e32 v13, v1, v11
	v_sub_f32_e32 v0, v1, v2
	v_mul_f32_e32 v2, v9, v13
	v_fma_f32 v4, v13, v9, -v2
	v_fmac_f32_e32 v4, v13, v10
	v_sub_f32_e32 v12, v3, v0
	v_add_f32_e32 v0, v2, v4
	v_sub_f32_e32 v3, v1, v0
	v_pk_add_f32 v[6:7], v[0:1], v[2:3] neg_lo:[0,1] neg_hi:[0,1]
	v_mov_b32_e32 v5, v0
	v_pk_add_f32 v[0:1], v[6:7], v[4:5] neg_lo:[0,1] neg_hi:[0,1]
	s_mov_b32 s3, 0x3f317218
	v_add_f32_e32 v1, v12, v1
	v_add_f32_e32 v0, v0, v1
	v_add_f32_e32 v1, v3, v0
	v_mul_f32_e32 v12, v11, v1
	v_mul_f32_e32 v2, v9, v12
	v_fma_f32 v4, v12, v9, -v2
	v_fmac_f32_e32 v4, v12, v10
	v_sub_f32_e32 v3, v3, v1
	v_add_f32_e32 v9, v0, v3
	v_add_f32_e32 v0, v2, v4
	v_sub_f32_e32 v3, v1, v0
	v_pk_add_f32 v[6:7], v[0:1], v[2:3] neg_lo:[0,1] neg_hi:[0,1]
	v_mov_b32_e32 v5, v0
	v_pk_add_f32 v[0:1], v[6:7], v[4:5] neg_lo:[0,1] neg_hi:[0,1]
	s_nop 0
	v_add_f32_e32 v1, v9, v1
	v_add_f32_e32 v0, v0, v1
	v_add_f32_e32 v1, v13, v12
	v_add_f32_e32 v0, v3, v0
	v_sub_f32_e32 v2, v1, v13
	v_mul_f32_e32 v0, v11, v0
	v_sub_f32_e32 v2, v12, v2
	v_add_f32_e32 v2, v2, v0
	v_add_f32_e32 v4, v1, v2
	v_mul_f32_e32 v5, v4, v4
	v_fmamk_f32 v0, v5, 0x3e9b6dac, v221
	v_fmaak_f32 v175, v5, v0, 0x3f2aaada
	v_cvt_f32_i32_e32 v0, v8
	v_sub_f32_e32 v1, v4, v1
	v_sub_f32_e32 v1, v2, v1
	v_ldexp_f32 v6, v1, 1
	v_mul_f32_e32 v1, v4, v5
	v_ldexp_f32 v3, v4, 1
	v_pk_mul_f32 v[4:5], v[0:1], v[174:175]
	s_nop 0
	v_fma_f32 v2, v0, s3, -v4
	v_fmac_f32_e32 v2, 0xb102e308, v0
	v_pk_add_f32 v[0:1], v[4:5], v[2:3]
	s_mov_b32 s3, 0x7f800000
	v_sub_f32_e32 v3, v1, v3
	v_sub_f32_e32 v3, v5, v3
	v_add_f32_e32 v7, v6, v3
	v_mov_b32_e32 v6, v4
	v_pk_add_f32 v[4:5], v[0:1], v[4:5] neg_lo:[0,1] neg_hi:[0,1]
	v_pk_add_f32 v[8:9], v[0:1], v[6:7]
	v_mov_b32_e32 v3, v0
	v_mov_b32_e32 v5, v9
	v_pk_add_f32 v[10:11], v[2:3], v[4:5] neg_lo:[0,1] neg_hi:[0,1]
	v_pk_add_f32 v[2:3], v[2:3], v[4:5]
	v_mov_b32_e32 v6, v7
	v_pk_add_f32 v[4:5], v[2:3], v[0:1] op_sel:[1,0] op_sel_hi:[0,1] neg_lo:[0,1] neg_hi:[0,1]
	v_pk_add_f32 v[12:13], v[8:9], v[4:5] op_sel_hi:[1,0] neg_lo:[0,1] neg_hi:[0,1]
	v_mov_b32_e32 v8, v9
	v_mov_b32_e32 v9, v3
	v_pk_mov_b32 v[4:5], v[0:1], v[4:5] op_sel:[1,0]
	v_mov_b32_e32 v7, v0
	v_pk_add_f32 v[4:5], v[8:9], v[4:5] neg_lo:[0,1] neg_hi:[0,1]
	v_mov_b32_e32 v12, v10
	v_pk_add_f32 v[0:1], v[6:7], v[4:5] neg_lo:[0,1] neg_hi:[0,1]
	v_mov_b32_e32 v11, v3
	v_pk_add_f32 v[4:5], v[12:13], v[0:1]
	v_cmp_neq_f32_e32 vcc, s3, v14
	v_pk_add_f32 v[6:7], v[4:5], v[4:5] op_sel:[0,1] op_sel_hi:[1,0]
	s_mov_b32 s3, 0x33800000
	v_pk_add_f32 v[2:3], v[2:3], v[6:7] op_sel:[1,0] op_sel_hi:[0,1]
	v_mov_b32_e32 v5, v2
	v_pk_add_f32 v[8:9], v[4:5], v[10:11] neg_lo:[0,1] neg_hi:[0,1]
	v_mov_b32_e32 v1, v6
	v_sub_f32_e32 v3, v4, v8
	v_pk_add_f32 v[0:1], v[0:1], v[8:9] neg_lo:[0,1] neg_hi:[0,1]
	v_sub_f32_e32 v3, v10, v3
	v_add_f32_e32 v0, v0, v3
	v_add_f32_e32 v0, v0, v1
	v_add_f32_e32 v0, v2, v0
	v_cndmask_b32_e32 v0, v249, v0, vcc
	v_cmp_ngt_f32_e32 vcc, -1.0, v14
	s_nop 1
	v_cndmask_b32_e32 v0, v250, v0, vcc
	v_cmp_neq_f32_e32 vcc, -1.0, v14
	s_nop 1
	v_cndmask_b32_e32 v0, v251, v0, vcc
	v_cmp_lt_f32_e64 vcc, |v14|, s3
	s_bfe_u32 s3, s12, 0x40001
	s_lshl_b32 s19, s3, 12
	s_lshl_b32 s6, s3, 13
	s_add_u32 s6, s20, s6
	s_addc_u32 s7, s21, 0
	v_lshl_add_u64 v[2:3], s[6:7], 0, v[48:49]
	v_lshl_add_u64 v[2:3], v[2:3], 0, v[108:109]
	s_mov_b32 s6, 0x20000
	v_cndmask_b32_e32 v0, v0, v14, vcc
	v_add_co_u32_e32 v4, vcc, s6, v2
	global_load_dwordx4 v[66:69], v[2:3], off
	s_nop 0
	v_addc_co_u32_e32 v5, vcc, 0, v3, vcc
	global_load_dwordx4 v[70:73], v[4:5], off
	global_load_dwordx4 v[74:77], v[2:3], off offset:32
	global_load_dwordx4 v[78:81], v[4:5], off offset:32
	global_load_dwordx4 v[82:85], v[2:3], off offset:64
	global_load_dwordx4 v[86:89], v[4:5], off offset:64
	global_load_dwordx4 v[90:93], v[2:3], off offset:96
	global_load_dwordx4 v[94:97], v[4:5], off offset:96
	s_lshl_b32 s29, s34, 12
	s_lshl_b32 s30, s34, 8
	s_lshl_b32 s36, s3, 6
	s_addk_i32 s29, 0xff00
	s_add_i32 s31, s30, 0x8000
	s_lshl_b32 s3, s3, 7
	s_add_u32 s8, s16, s3
	s_addc_u32 s9, s17, 0
	v_mul_f32_e32 v118, 0xc138aa3b, v0
	s_cmp_eq_u32 s35, 0
	v_lshl_or_b32 v48, s2, 11, v178
	v_lshl_add_u64 v[120:121], s[8:9], 0, v[108:109]
	s_cselect_b64 s[56:57], -1, 0
	v_mov_b32_e32 v119, v118
	s_mulk_i32 s34, 0x88
	v_lshl_add_u64 v[112:113], s[64:65], 0, v[48:49]
	s_sub_i32 s37, s25, s30
	s_mov_b64 s[100:101], s[8:9]
	s_lshr_b32 s98, s22, 1
	s_mulk_i32 s98, 0x1200
	s_add_i32 s98, s98, 0x8000
	v_and_b32_e32 v240, 63, v220
	v_lshrrev_b32_e32 v241, 3, v240
	v_and_b32_e32 v240, 7, v240
	v_lshlrev_b32_e32 v240, 4, v240
	v_lshl_add_u32 v234, v241, 11, v240
	v_add_u32_e32 v235, 0x4000, v234
	v_add_u32_e32 v236, 0x8000, v234
	v_add_u32_e32 v237, 0xc000, v234
	v_mul_u32_u24_e32 v241, 0x90, v241
	v_add3_u32 v238, v241, v240, s98
	v_and_b32_e32 v240, 63, v103
	v_mul_u32_u24_e32 v240, 0x90, v240
	v_bfe_u32 v241, v220, 5, 1
	v_lshl_add_u32 v241, v241, 4, v240
	v_add_u32_e32 v239, s98, v241
	s_branch .LBB0_22

; template <int DIR>
; __device__ __forceinline__ void lru_dir(const bf16_t* XR, const bf16_t* GATE, bf16_t* YP, u32x4* HSF, const bf16_t* bdw_dir, float bias_r, float bias_i, float sp,
;                                         int b, int n2, int lane, int wave, LAS float* xl) {
;     ...
;         for (int k = 0; k < 2; ++k) {
;             const int q = seg * 16 + wave * 2 + k; valid[k] = q < 136;
;             const int T = DIR == 0 ? q : (q < 8 ? 7 - q : 143 - q);
;             trow[k] = T < 8 ? ML + b * CTXL + 32 * T : b * SEQ + 32 * (T - 8);
;             if (valid[k]) {
;                 const bf16_t* ap = XR + (size_t)(trow[k] + tau) * DM + n * 64 + 8 * hh;
;                 bf16x8 A[4];
; #pragma unroll
;                 for (int kk = 0; kk < 4; ++kk) A[kk] = *(const bf16x8*)(ap + 16 * kk);
;                 f32x16 ar, ai, xv;
; #pragma unroll
;                 for (int r = 0; r < 16; ++r) { ar[r] = 0.f; ai[r] = 0.f; xv[r] = 0.f; }
; #pragma unroll
;                 for (int kk = 0; kk < 4; ++kk) { ar = mfma32(A[kk], Br[kk], ar); ai = mfma32(A[kk], Bi[kk], ai); }
;                 const bf16x8 Ax0 = half ? A[2] : A[0], Ax1 = half ? A[3] : A[1];
;                 xv = mfma32(Ax0, I0, xv); xv = mfma32(Ax1, I1, xv);
;                 typedef float f32x2 __attribute__((ext_vector_type(2)));
; #pragma unroll
;                 for (int r = 0; r < 16; r += 2) {
;                     const f32x2 er = ((f32x2){ar[r], ar[r + 1]} + bias_r) * -1.4426950408889634f, ei = ((f32x2){ai[r], ai[r + 1]} + bias_i) * -1.4426950408889634f;
;                     const f32x2 dr = (f32x2){__builtin_amdgcn_exp2f(er[0]), __builtin_amdgcn_exp2f(er[1])} + 1.0f, di = (f32x2){__builtin_amdgcn_exp2f(ei[0]), __builtin_amdgcn_exp2f(ei[1])} + 1.0f;
;                     const f32x2 rg = {__builtin_amdgcn_rcpf(dr[0]), __builtin_amdgcn_rcpf(dr[1])}, ig = {__builtin_amdgcn_rcpf(di[0]), __builtin_amdgcn_rcpf(di[1])};
;                     const f32x2 la = rg * spm;
;                     const f32x2 aa = {__builtin_amdgcn_exp2f(la[0]), __builtin_amdgcn_exp2f(la[1])};
;                     const f32x2 om = __builtin_elementwise_max(1.0f - aa * aa, (f32x2){0.f, 0.f});
;                     const f32x2 bb = (f32x2){__builtin_amdgcn_sqrtf(om[0]), __builtin_amdgcn_sqrtf(om[1])} * ig * (f32x2){xv[r], xv[r + 1]};
.LBB0_24:
	s_andn2_b64 vcc, exec, s[2:3]
	s_cbranch_vccnz .LBB0_26
	s_add_i32 s2, s39, s59
	v_add_u32_e32 v0, s2, v103
	v_ashrrev_i32_e32 v1, 31, v0
	v_lshlrev_b64 v[0:1], 11, v[0:1]
	v_lshl_add_u64 v[12:13], v[120:121], 0, v[0:1]
	s_add_i32 s98, s39, s59
	s_add_i32 s98, s98, s25
	s_lshl_b32 s98, s98, 11
	s_add_u32 s98, s100, s98
	s_addc_u32 s99, s101, 0
	global_load_dwordx4 v[0:3], v234, s[98:99]
	global_load_dwordx4 v[4:7], v235, s[98:99]
	global_load_dwordx4 v[8:11], v236, s[98:99]
	global_load_dwordx4 v[12:15], v237, s[98:99]
	s_waitcnt vmcnt(3)
	ds_write_b128 v238, v[0:3]
	s_waitcnt vmcnt(2)
	ds_write_b128 v238, v[4:7] offset:1152
	s_waitcnt vmcnt(1)
	ds_write_b128 v238, v[8:11] offset:2304
	s_waitcnt vmcnt(0)
	ds_write_b128 v238, v[12:15] offset:3456
	ds_read_b128 v[0:3], v239
	ds_read_b128 v[4:7], v239 offset:32
	ds_read_b128 v[8:11], v239 offset:64
	ds_read_b128 v[12:15], v239 offset:96
	s_waitcnt lgkmcnt(0)
	v_mfma_f32_32x32x16_bf16 v[32:47], v[0:3], v[66:69], 0
	s_waitcnt vmcnt(0)
	v_cndmask_b32_e64 v125, v15, v7, s[56:57]
	v_cndmask_b32_e64 v124, v14, v6, s[56:57]
	v_cndmask_b32_e64 v123, v13, v5, s[56:57]
	v_cndmask_b32_e64 v122, v12, v4, s[56:57]
	v_mfma_f32_32x32x16_bf16 v[32:47], v[4:7], v[74:77], v[32:47]
	v_mfma_f32_32x32x16_bf16 v[16:31], v[0:3], v[70:73], 0
	v_cndmask_b32_e64 v3, v11, v3, s[56:57]
	v_cndmask_b32_e64 v2, v10, v2, s[56:57]
	v_cndmask_b32_e64 v1, v9, v1, s[56:57]
	v_cndmask_b32_e64 v0, v8, v0, s[56:57]
	v_mfma_f32_32x32x16_bf16 v[32:47], v[8:11], v[82:85], v[32:47]
	v_mfma_f32_32x32x16_bf16 v[16:31], v[4:7], v[78:81], v[16:31]
	v_mfma_f32_32x32x16_bf16 v[32:47], v[12:15], v[90:93], v[32:47]
	v_mfma_f32_32x32x16_bf16 v[16:31], v[8:11], v[86:89], v[16:31]
	s_nop 10
	v_add_f32_e64 v32, v114, v32
	v_add_f32_e64 v33, v115, v33
	v_mul_f32_e64 v32, v32, s14
	v_mul_f32_e64 v33, v33, s14
	v_exp_f32_e32 v32, v32
	v_exp_f32_e32 v33, v33
	v_mfma_f32_32x32x16_bf16 v[16:31], v[12:15], v[94:97], v[16:31]
	v_add_f32_e64 v32, v32, 1.0
	v_add_f32_e64 v33, v33, 1.0
	v_rcp_f32_e32 v32, v32
	v_rcp_f32_e32 v33, v33
	s_nop 0
	v_pk_mul_f32 v[32:33], v[118:119], v[32:33]
	v_mfma_f32_32x32x16_bf16 v[0:15], v[0:3], v[50:53], 0
	s_nop 4
	v_add_f32_e64 v16, v116, v16
	v_add_f32_e64 v17, v117, v17
	v_mul_f32_e64 v16, v16, s14
	v_mul_f32_e64 v17, v17, s14
	v_exp_f32_e32 v16, v16
	v_exp_f32_e32 v17, v17
	v_mfma_f32_32x32x16_bf16 v[0:15], v[122:125], v[54:57], v[0:15]
	v_exp_f32_e32 v124, v32
	v_exp_f32_e32 v125, v33
	v_pk_add_f32 v[16:17], v[16:17], 1.0 op_sel_hi:[1,0]
	v_pk_fma_f32 v[32:33], v[124:125], v[124:125], 1.0 op_sel_hi:[1,1,0] neg_lo:[1,0,0] neg_hi:[1,0,0]
	s_nop 0
	v_max_f32_e32 v33, 0, v33
	v_max_f32_e32 v32, 0, v32
	v_rcp_f32_e32 v16, v16
	v_rcp_f32_e32 v17, v17
	v_sqrt_f32_e32 v32, v32
	v_sqrt_f32_e32 v33, v33
	s_nop 0
	v_pk_mul_f32 v[16:17], v[16:17], v[32:33]
	s_nop 0
	v_pk_mul_f32 v[122:123], v[0:1], v[16:17]
	v_pk_add_f32 v[0:1], v[114:115], v[34:35]
	v_pk_add_f32 v[16:17], v[116:117], v[18:19]
	v_pk_mul_f32 v[0:1], v[0:1], s[14:15] op_sel_hi:[1,0]
	v_pk_mul_f32 v[16:17], v[16:17], s[14:15] op_sel_hi:[1,0]
	v_exp_f32_e32 v0, v0
	v_exp_f32_e32 v1, v1
	v_exp_f32_e32 v16, v16
	v_exp_f32_e32 v17, v17
	v_pk_add_f32 v[0:1], v[0:1], 1.0 op_sel_hi:[1,0]
	s_nop 0
	v_rcp_f32_e32 v0, v0
	v_rcp_f32_e32 v1, v1
	v_pk_add_f32 v[16:17], v[16:17], 1.0 op_sel_hi:[1,0]
	v_pk_mul_f32 v[0:1], v[118:119], v[0:1]
	s_nop 0
	v_exp_f32_e32 v128, v0
	v_exp_f32_e32 v129, v1
	v_rcp_f32_e32 v16, v16
	v_rcp_f32_e32 v17, v17
	v_pk_fma_f32 v[0:1], v[128:129], v[128:129], 1.0 op_sel_hi:[1,1,0] neg_lo:[1,0,0] neg_hi:[1,0,0]
	s_nop 0
	v_max_f32_e32 v1, 0, v1
	v_max_f32_e32 v0, 0, v0
	v_sqrt_f32_e32 v0, v0
	v_sqrt_f32_e32 v1, v1
	s_nop 0
	v_pk_mul_f32 v[0:1], v[16:17], v[0:1]
	s_nop 0
	v_pk_mul_f32 v[126:127], v[2:3], v[0:1]
	v_pk_add_f32 v[0:1], v[114:115], v[36:37]
	v_pk_add_f32 v[2:3], v[116:117], v[20:21]
	v_pk_mul_f32 v[0:1], v[0:1], s[14:15] op_sel_hi:[1,0]
	v_pk_mul_f32 v[2:3], v[2:3], s[14:15] op_sel_hi:[1,0]
	v_exp_f32_e32 v0, v0
	v_exp_f32_e32 v1, v1
	v_exp_f32_e32 v2, v2
	v_exp_f32_e32 v3, v3
	v_pk_add_f32 v[0:1], v[0:1], 1.0 op_sel_hi:[1,0]
	s_nop 0
	v_rcp_f32_e32 v0, v0
	v_rcp_f32_e32 v1, v1
	v_pk_add_f32 v[2:3], v[2:3], 1.0 op_sel_hi:[1,0]
	v_pk_mul_f32 v[0:1], v[118:119], v[0:1]
	s_nop 0
	v_exp_f32_e32 v132, v0
	v_exp_f32_e32 v133, v1
	v_rcp_f32_e32 v2, v2
	v_rcp_f32_e32 v3, v3
	v_pk_fma_f32 v[0:1], v[132:133], v[132:133], 1.0 op_sel_hi:[1,1,0] neg_lo:[1,0,0] neg_hi:[1,0,0]
	s_nop 0
	v_max_f32_e32 v1, 0, v1
	v_max_f32_e32 v0, 0, v0
	v_sqrt_f32_e32 v0, v0
; template <int DIR>
; __device__ __forceinline__ void lru_dir(const bf16_t* XR, const bf16_t* GATE, bf16_t* YP, u32x4* HSF, const bf16_t* bdw_dir, float bias_r, float bias_i, float sp,
;                                         int b, int n2, int lane, int wave, LAS float* xl) {
;     ...
;                 for (int r = 0; r < 16; r += 2) {
;                     const f32x2 er = ((f32x2){ar[r], ar[r + 1]} + bias_r) * -1.4426950408889634f, ei = ((f32x2){ai[r], ai[r + 1]} + bias_i) * -1.4426950408889634f;
;                     const f32x2 dr = (f32x2){__builtin_amdgcn_exp2f(er[0]), __builtin_amdgcn_exp2f(er[1])} + 1.0f, di = (f32x2){__builtin_amdgcn_exp2f(ei[0]), __builtin_amdgcn_exp2f(ei[1])} + 1.0f;
;                     const f32x2 rg = {__builtin_amdgcn_rcpf(dr[0]), __builtin_amdgcn_rcpf(dr[1])}, ig = {__builtin_amdgcn_rcpf(di[0]), __builtin_amdgcn_rcpf(di[1])};
;                     const f32x2 la = rg * spm;
;                     const f32x2 aa = {__builtin_amdgcn_exp2f(la[0]), __builtin_amdgcn_exp2f(la[1])};
;                     const f32x2 om = __builtin_elementwise_max(1.0f - aa * aa, (f32x2){0.f, 0.f});
;                     const f32x2 bb = (f32x2){__builtin_amdgcn_sqrtf(om[0]), __builtin_amdgcn_sqrtf(om[1])} * ig * (f32x2){xv[r], xv[r + 1]};
;                     av[k][r] = aa[0]; av[k][r + 1] = aa[1]; bv[k][r] = bb[0]; bv[k][r + 1] = bb[1];
;                 }
	v_sqrt_f32_e32 v1, v1
	s_nop 0
	v_pk_mul_f32 v[0:1], v[2:3], v[0:1]
	s_nop 0
	v_pk_mul_f32 v[130:131], v[4:5], v[0:1]
	v_pk_add_f32 v[0:1], v[114:115], v[38:39]
	v_pk_add_f32 v[2:3], v[116:117], v[22:23]
	v_pk_mul_f32 v[0:1], v[0:1], s[14:15] op_sel_hi:[1,0]
	v_pk_mul_f32 v[2:3], v[2:3], s[14:15] op_sel_hi:[1,0]
	v_exp_f32_e32 v0, v0
	v_exp_f32_e32 v1, v1
	v_exp_f32_e32 v2, v2
	v_exp_f32_e32 v3, v3
	v_pk_add_f32 v[0:1], v[0:1], 1.0 op_sel_hi:[1,0]
	s_nop 0
	v_rcp_f32_e32 v0, v0
	v_rcp_f32_e32 v1, v1
	v_pk_add_f32 v[2:3], v[2:3], 1.0 op_sel_hi:[1,0]
	v_pk_mul_f32 v[0:1], v[118:119], v[0:1]
	s_nop 0
	v_exp_f32_e32 v136, v0
	v_exp_f32_e32 v137, v1
	v_rcp_f32_e32 v2, v2
	v_rcp_f32_e32 v3, v3
	v_pk_fma_f32 v[0:1], v[136:137], v[136:137], 1.0 op_sel_hi:[1,1,0] neg_lo:[1,0,0] neg_hi:[1,0,0]
	s_nop 0
	v_max_f32_e32 v1, 0, v1
	v_max_f32_e32 v0, 0, v0
	v_sqrt_f32_e32 v0, v0
	v_sqrt_f32_e32 v1, v1
	s_nop 0
	v_pk_mul_f32 v[0:1], v[2:3], v[0:1]
	s_nop 0
	v_pk_mul_f32 v[134:135], v[6:7], v[0:1]
	v_pk_add_f32 v[0:1], v[114:115], v[40:41]
	v_pk_add_f32 v[2:3], v[116:117], v[24:25]
	v_pk_mul_f32 v[0:1], v[0:1], s[14:15] op_sel_hi:[1,0]
	v_pk_mul_f32 v[2:3], v[2:3], s[14:15] op_sel_hi:[1,0]
	v_exp_f32_e32 v0, v0
	v_exp_f32_e32 v1, v1
	v_exp_f32_e32 v2, v2
	v_exp_f32_e32 v3, v3
	v_pk_add_f32 v[0:1], v[0:1], 1.0 op_sel_hi:[1,0]
	s_nop 0
	v_rcp_f32_e32 v0, v0
	v_rcp_f32_e32 v1, v1
	v_pk_add_f32 v[2:3], v[2:3], 1.0 op_sel_hi:[1,0]
	v_pk_mul_f32 v[0:1], v[118:119], v[0:1]
	s_nop 0
	v_exp_f32_e32 v140, v0
	v_exp_f32_e32 v141, v1
	v_rcp_f32_e32 v2, v2
	v_rcp_f32_e32 v3, v3
	v_pk_fma_f32 v[0:1], v[140:141], v[140:141], 1.0 op_sel_hi:[1,1,0] neg_lo:[1,0,0] neg_hi:[1,0,0]
	s_nop 0
	v_max_f32_e32 v1, 0, v1
	v_max_f32_e32 v0, 0, v0
	v_sqrt_f32_e32 v0, v0
	v_sqrt_f32_e32 v1, v1
	s_nop 0
	v_pk_mul_f32 v[0:1], v[2:3], v[0:1]
	s_nop 0
	v_pk_mul_f32 v[138:139], v[8:9], v[0:1]
	v_pk_add_f32 v[0:1], v[114:115], v[42:43]
	v_pk_add_f32 v[2:3], v[116:117], v[26:27]
	v_pk_mul_f32 v[0:1], v[0:1], s[14:15] op_sel_hi:[1,0]
	v_pk_mul_f32 v[2:3], v[2:3], s[14:15] op_sel_hi:[1,0]
	v_exp_f32_e32 v0, v0
	v_exp_f32_e32 v1, v1
	v_exp_f32_e32 v2, v2
	v_exp_f32_e32 v3, v3
	v_pk_add_f32 v[0:1], v[0:1], 1.0 op_sel_hi:[1,0]
	s_nop 0
	v_rcp_f32_e32 v0, v0
	v_rcp_f32_e32 v1, v1
	v_pk_add_f32 v[2:3], v[2:3], 1.0 op_sel_hi:[1,0]
	v_pk_mul_f32 v[0:1], v[118:119], v[0:1]
	s_nop 0
	v_exp_f32_e32 v144, v0
	v_exp_f32_e32 v145, v1
	v_rcp_f32_e32 v2, v2
	v_rcp_f32_e32 v3, v3
	v_pk_fma_f32 v[0:1], v[144:145], v[144:145], 1.0 op_sel_hi:[1,1,0] neg_lo:[1,0,0] neg_hi:[1,0,0]
	s_nop 0
	v_max_f32_e32 v1, 0, v1
	v_max_f32_e32 v0, 0, v0
	v_sqrt_f32_e32 v0, v0
	v_sqrt_f32_e32 v1, v1
	s_nop 0
	v_pk_mul_f32 v[0:1], v[2:3], v[0:1]
	s_nop 0
	v_pk_mul_f32 v[142:143], v[10:11], v[0:1]
	v_pk_add_f32 v[0:1], v[114:115], v[44:45]
	v_pk_add_f32 v[2:3], v[116:117], v[28:29]
	v_pk_mul_f32 v[0:1], v[0:1], s[14:15] op_sel_hi:[1,0]
	v_pk_mul_f32 v[2:3], v[2:3], s[14:15] op_sel_hi:[1,0]
	v_exp_f32_e32 v0, v0
	v_exp_f32_e32 v1, v1
	v_exp_f32_e32 v2, v2
	v_exp_f32_e32 v3, v3
	v_pk_add_f32 v[0:1], v[0:1], 1.0 op_sel_hi:[1,0]
	s_nop 0
	v_rcp_f32_e32 v0, v0
	v_rcp_f32_e32 v1, v1
	v_pk_add_f32 v[2:3], v[2:3], 1.0 op_sel_hi:[1,0]
	v_pk_mul_f32 v[0:1], v[118:119], v[0:1]
	s_nop 0
	v_exp_f32_e32 v148, v0
	v_exp_f32_e32 v149, v1
	v_rcp_f32_e32 v2, v2
	v_rcp_f32_e32 v3, v3
	v_pk_fma_f32 v[0:1], v[148:149], v[148:149], 1.0 op_sel_hi:[1,1,0] neg_lo:[1,0,0] neg_hi:[1,0,0]
	s_nop 0
	v_max_f32_e32 v1, 0, v1
	v_max_f32_e32 v0, 0, v0
	v_sqrt_f32_e32 v0, v0
	v_sqrt_f32_e32 v1, v1
	s_nop 0
	v_pk_mul_f32 v[0:1], v[2:3], v[0:1]
	s_nop 0
	v_pk_mul_f32 v[146:147], v[12:13], v[0:1]
	v_pk_add_f32 v[0:1], v[114:115], v[46:47]
	v_pk_add_f32 v[2:3], v[116:117], v[30:31]
	v_pk_mul_f32 v[0:1], v[0:1], s[14:15] op_sel_hi:[1,0]
	v_pk_mul_f32 v[2:3], v[2:3], s[14:15] op_sel_hi:[1,0]
	v_exp_f32_e32 v0, v0
	v_exp_f32_e32 v1, v1
	v_exp_f32_e32 v2, v2
	v_exp_f32_e32 v3, v3
	v_pk_add_f32 v[0:1], v[0:1], 1.0 op_sel_hi:[1,0]
	s_nop 0
	v_rcp_f32_e32 v0, v0
	v_rcp_f32_e32 v1, v1
	v_pk_add_f32 v[2:3], v[2:3], 1.0 op_sel_hi:[1,0]
	v_pk_mul_f32 v[0:1], v[118:119], v[0:1]
	s_nop 0
	v_exp_f32_e32 v152, v0
	v_exp_f32_e32 v153, v1
	v_rcp_f32_e32 v2, v2
	v_rcp_f32_e32 v3, v3
	v_pk_fma_f32 v[0:1], v[152:153], v[152:153], 1.0 op_sel_hi:[1,1,0] neg_lo:[1,0,0] neg_hi:[1,0,0]
	s_nop 0
	v_max_f32_e32 v1, 0, v1
	v_max_f32_e32 v0, 0, v0
	v_sqrt_f32_e32 v0, v0
	v_sqrt_f32_e32 v1, v1
	s_nop 0
	v_pk_mul_f32 v[0:1], v[2:3], v[0:1]
	s_nop 0
	v_pk_mul_f32 v[150:151], v[14:15], v[0:1]
	s_branch .LBB0_27

; template <int DIR>
; __device__ __forceinline__ void lru_dir(const bf16_t* XR, const bf16_t* GATE, bf16_t* YP, u32x4* HSF, const bf16_t* bdw_dir, float bias_r, float bias_i, float sp,
;                                         int b, int n2, int lane, int wave, LAS float* xl) {
;     ...
;         for (int k = 0; k < 2; ++k) {
;             const int q = seg * 16 + wave * 2 + k; valid[k] = q < 136;
;             const int T = DIR == 0 ? q : (q < 8 ? 7 - q : 143 - q);
;             trow[k] = T < 8 ? ML + b * CTXL + 32 * T : b * SEQ + 32 * (T - 8);
;             if (valid[k]) {
;                 const bf16_t* ap = XR + (size_t)(trow[k] + tau) * DM + n * 64 + 8 * hh;
;                 bf16x8 A[4];
; #pragma unroll
;                 for (int kk = 0; kk < 4; ++kk) A[kk] = *(const bf16x8*)(ap + 16 * kk);
;                 f32x16 ar, ai, xv;
; #pragma unroll
;                 for (int r = 0; r < 16; ++r) { ar[r] = 0.f; ai[r] = 0.f; xv[r] = 0.f; }
; #pragma unroll
;                 for (int kk = 0; kk < 4; ++kk) { ar = mfma32(A[kk], Br[kk], ar); ai = mfma32(A[kk], Bi[kk], ai); }
;                 const bf16x8 Ax0 = half ? A[2] : A[0], Ax1 = half ? A[3] : A[1];
;                 xv = mfma32(Ax0, I0, xv); xv = mfma32(Ax1, I1, xv);
;                 typedef float f32x2 __attribute__((ext_vector_type(2)));
; #pragma unroll
;                 for (int r = 0; r < 16; r += 2) {
;                     const f32x2 er = ((f32x2){ar[r], ar[r + 1]} + bias_r) * -1.4426950408889634f, ei = ((f32x2){ai[r], ai[r + 1]} + bias_i) * -1.4426950408889634f;
;                     const f32x2 dr = (f32x2){__builtin_amdgcn_exp2f(er[0]), __builtin_amdgcn_exp2f(er[1])} + 1.0f, di = (f32x2){__builtin_amdgcn_exp2f(ei[0]), __builtin_amdgcn_exp2f(ei[1])} + 1.0f;
;                     const f32x2 rg = {__builtin_amdgcn_rcpf(dr[0]), __builtin_amdgcn_rcpf(dr[1])}, ig = {__builtin_amdgcn_rcpf(di[0]), __builtin_amdgcn_rcpf(di[1])};
;                     const f32x2 la = rg * spm;
;                     const f32x2 aa = {__builtin_amdgcn_exp2f(la[0]), __builtin_amdgcn_exp2f(la[1])};
;                     const f32x2 om = __builtin_elementwise_max(1.0f - aa * aa, (f32x2){0.f, 0.f});
;                     const f32x2 bb = (f32x2){__builtin_amdgcn_sqrtf(om[0]), __builtin_amdgcn_sqrtf(om[1])} * ig * (f32x2){xv[r], xv[r + 1]};
.LBB0_29:
	s_andn2_b64 vcc, exec, s[6:7]
	s_cbranch_vccnz .LBB0_31
	s_add_i32 s6, s39, s63
	v_add3_u32 v0, s6, v103, 32
	v_ashrrev_i32_e32 v1, 31, v0
	v_lshlrev_b64 v[0:1], 11, v[0:1]
	v_lshl_add_u64 v[12:13], v[120:121], 0, v[0:1]
	s_add_i32 s98, s39, s63
	s_add_i32 s98, s98, s25
	s_add_i32 s98, s98, 32
	s_lshl_b32 s98, s98, 11
	s_add_u32 s98, s100, s98
	s_addc_u32 s99, s101, 0
	global_load_dwordx4 v[0:3], v234, s[98:99]
	global_load_dwordx4 v[4:7], v235, s[98:99]
	global_load_dwordx4 v[8:11], v236, s[98:99]
	global_load_dwordx4 v[12:15], v237, s[98:99]
	s_waitcnt vmcnt(3)
	ds_write_b128 v238, v[0:3]
	s_waitcnt vmcnt(2)
	ds_write_b128 v238, v[4:7] offset:1152
	s_waitcnt vmcnt(1)
	ds_write_b128 v238, v[8:11] offset:2304
	s_waitcnt vmcnt(0)
	ds_write_b128 v238, v[12:15] offset:3456
	ds_read_b128 v[0:3], v239
	ds_read_b128 v[4:7], v239 offset:32
	ds_read_b128 v[8:11], v239 offset:64
	ds_read_b128 v[12:15], v239 offset:96
	s_waitcnt lgkmcnt(0)
	v_mfma_f32_32x32x16_bf16 v[32:47], v[0:3], v[66:69], 0
	s_waitcnt vmcnt(0)
	v_cndmask_b32_e64 v157, v15, v7, s[56:57]
	v_cndmask_b32_e64 v156, v14, v6, s[56:57]
	v_cndmask_b32_e64 v155, v13, v5, s[56:57]
	v_cndmask_b32_e64 v154, v12, v4, s[56:57]
	v_mfma_f32_32x32x16_bf16 v[16:31], v[0:3], v[70:73], 0
	v_cndmask_b32_e64 v3, v11, v3, s[56:57]
	v_cndmask_b32_e64 v2, v10, v2, s[56:57]
	v_cndmask_b32_e64 v1, v9, v1, s[56:57]
	v_cndmask_b32_e64 v0, v8, v0, s[56:57]
	v_mfma_f32_32x32x16_bf16 v[32:47], v[4:7], v[74:77], v[32:47]
	v_mfma_f32_32x32x16_bf16 v[16:31], v[4:7], v[78:81], v[16:31]
	v_mfma_f32_32x32x16_bf16 v[32:47], v[8:11], v[82:85], v[32:47]
	v_mfma_f32_32x32x16_bf16 v[16:31], v[8:11], v[86:89], v[16:31]
	v_mfma_f32_32x32x16_bf16 v[32:47], v[12:15], v[90:93], v[32:47]
	v_mfma_f32_32x32x16_bf16 v[16:31], v[12:15], v[94:97], v[16:31]
	s_nop 10
	v_add_f32_e64 v32, v114, v32
	v_add_f32_e64 v33, v115, v33
	v_mul_f32_e64 v32, v32, s14
	v_mul_f32_e64 v33, v33, s14
	v_exp_f32_e32 v32, v32
	v_exp_f32_e32 v33, v33
	v_pk_add_f32 v[16:17], v[116:117], v[16:17]
	v_mfma_f32_32x32x16_bf16 v[0:15], v[0:3], v[50:53], 0
	v_mul_f32_e64 v16, v16, s14
	v_mul_f32_e64 v17, v17, s14
	v_add_f32_e64 v32, v32, 1.0
	v_add_f32_e64 v33, v33, 1.0
	v_exp_f32_e32 v16, v16
	v_exp_f32_e32 v17, v17
	v_rcp_f32_e32 v32, v32
	v_rcp_f32_e32 v33, v33
	v_pk_add_f32 v[18:19], v[116:117], v[18:19]
	v_pk_add_f32 v[16:17], v[16:17], 1.0 op_sel_hi:[1,0]
	v_mfma_f32_32x32x16_bf16 v[0:15], v[154:157], v[54:57], v[0:15]
	v_rcp_f32_e32 v154, v16
	v_rcp_f32_e32 v155, v17
	v_pk_mul_f32 v[16:17], v[118:119], v[32:33]
	v_pk_mul_f32 v[18:19], v[18:19], s[14:15] op_sel_hi:[1,0]
	v_exp_f32_e32 v16, v16
	v_exp_f32_e32 v17, v17
	v_exp_f32_e32 v18, v18
	v_exp_f32_e32 v19, v19
	v_pk_add_f32 v[20:21], v[116:117], v[20:21]
	v_pk_fma_f32 v[32:33], v[16:17], v[16:17], 1.0 op_sel_hi:[1,1,0] neg_lo:[1,0,0] neg_hi:[1,0,0]
	v_pk_mul_f32 v[20:21], v[20:21], s[14:15] op_sel_hi:[1,0]
	v_max_f32_e32 v33, 0, v33
	v_max_f32_e32 v32, 0, v32
	v_sqrt_f32_e32 v32, v32
	v_sqrt_f32_e32 v33, v33
	v_pk_add_f32 v[18:19], v[18:19], 1.0 op_sel_hi:[1,0]
	v_exp_f32_e32 v20, v20
	v_exp_f32_e32 v21, v21
	v_pk_mul_f32 v[32:33], v[154:155], v[32:33]
	v_pk_add_f32 v[22:23], v[116:117], v[22:23]
	v_pk_mul_f32 v[0:1], v[0:1], v[32:33]
	v_pk_add_f32 v[32:33], v[114:115], v[34:35]
	v_rcp_f32_e32 v34, v18
	v_pk_mul_f32 v[32:33], v[32:33], s[14:15] op_sel_hi:[1,0]
	v_rcp_f32_e32 v35, v19
	v_exp_f32_e32 v32, v32
	v_exp_f32_e32 v33, v33
	v_pk_add_f32 v[20:21], v[20:21], 1.0 op_sel_hi:[1,0]
	v_pk_mul_f32 v[22:23], v[22:23], s[14:15] op_sel_hi:[1,0]
	v_pk_add_f32 v[24:25], v[116:117], v[24:25]
	v_pk_add_f32 v[32:33], v[32:33], 1.0 op_sel_hi:[1,0]
	v_exp_f32_e32 v22, v22
	v_rcp_f32_e32 v32, v32
	v_rcp_f32_e32 v33, v33
	v_exp_f32_e32 v23, v23
	v_pk_mul_f32 v[24:25], v[24:25], s[14:15] op_sel_hi:[1,0]
	v_pk_add_f32 v[26:27], v[116:117], v[26:27]
	v_pk_mul_f32 v[18:19], v[118:119], v[32:33]
	v_pk_add_f32 v[22:23], v[22:23], 1.0 op_sel_hi:[1,0]
	v_exp_f32_e32 v18, v18
	v_exp_f32_e32 v19, v19
	v_exp_f32_e32 v24, v24
	v_exp_f32_e32 v25, v25
	v_pk_mul_f32 v[26:27], v[26:27], s[14:15] op_sel_hi:[1,0]
	v_pk_fma_f32 v[32:33], v[18:19], v[18:19], 1.0 op_sel_hi:[1,1,0] neg_lo:[1,0,0] neg_hi:[1,0,0]
	v_exp_f32_e32 v26, v26
	v_max_f32_e32 v33, 0, v33
	v_max_f32_e32 v32, 0, v32
	v_sqrt_f32_e32 v32, v32
	v_sqrt_f32_e32 v33, v33
	v_pk_add_f32 v[24:25], v[24:25], 1.0 op_sel_hi:[1,0]
	v_exp_f32_e32 v27, v27
	v_pk_add_f32 v[28:29], v[116:117], v[28:29]
	v_pk_mul_f32 v[32:33], v[34:35], v[32:33]
	v_rcp_f32_e32 v34, v20
	v_pk_mul_f32 v[2:3], v[2:3], v[32:33]
	v_pk_add_f32 v[32:33], v[114:115], v[36:37]
	v_rcp_f32_e32 v35, v21
	v_pk_mul_f32 v[32:33], v[32:33], s[14:15] op_sel_hi:[1,0]
	v_pk_add_f32 v[26:27], v[26:27], 1.0 op_sel_hi:[1,0]
; template <int DIR>
; __device__ __forceinline__ void lru_dir(const bf16_t* XR, const bf16_t* GATE, bf16_t* YP, u32x4* HSF, const bf16_t* bdw_dir, float bias_r, float bias_i, float sp,
;                                         int b, int n2, int lane, int wave, LAS float* xl) {
;     ...
;                 for (int r = 0; r < 16; r += 2) {
;                     const f32x2 er = ((f32x2){ar[r], ar[r + 1]} + bias_r) * -1.4426950408889634f, ei = ((f32x2){ai[r], ai[r + 1]} + bias_i) * -1.4426950408889634f;
;                     const f32x2 dr = (f32x2){__builtin_amdgcn_exp2f(er[0]), __builtin_amdgcn_exp2f(er[1])} + 1.0f, di = (f32x2){__builtin_amdgcn_exp2f(ei[0]), __builtin_amdgcn_exp2f(ei[1])} + 1.0f;
;                     const f32x2 rg = {__builtin_amdgcn_rcpf(dr[0]), __builtin_amdgcn_rcpf(dr[1])}, ig = {__builtin_amdgcn_rcpf(di[0]), __builtin_amdgcn_rcpf(di[1])};
;                     const f32x2 la = rg * spm;
;                     const f32x2 aa = {__builtin_amdgcn_exp2f(la[0]), __builtin_amdgcn_exp2f(la[1])};
;                     const f32x2 om = __builtin_elementwise_max(1.0f - aa * aa, (f32x2){0.f, 0.f});
;                     const f32x2 bb = (f32x2){__builtin_amdgcn_sqrtf(om[0]), __builtin_amdgcn_sqrtf(om[1])} * ig * (f32x2){xv[r], xv[r + 1]};
;                     av[k][r] = aa[0]; av[k][r + 1] = aa[1]; bv[k][r] = bb[0]; bv[k][r + 1] = bb[1];
;                 }
	v_exp_f32_e32 v32, v32
	v_exp_f32_e32 v33, v33
	v_pk_mul_f32 v[28:29], v[28:29], s[14:15] op_sel_hi:[1,0]
	v_pk_add_f32 v[30:31], v[116:117], v[30:31]
	v_exp_f32_e32 v28, v28
	v_pk_add_f32 v[32:33], v[32:33], 1.0 op_sel_hi:[1,0]
	v_exp_f32_e32 v29, v29
	v_rcp_f32_e32 v32, v32
	v_rcp_f32_e32 v33, v33
	v_pk_mul_f32 v[30:31], v[30:31], s[14:15] op_sel_hi:[1,0]
	v_pk_add_f32 v[28:29], v[28:29], 1.0 op_sel_hi:[1,0]
	v_exp_f32_e32 v30, v30
	v_pk_mul_f32 v[20:21], v[118:119], v[32:33]
	v_exp_f32_e32 v31, v31
	v_exp_f32_e32 v20, v20
	v_exp_f32_e32 v21, v21
	v_pk_add_f32 v[30:31], v[30:31], 1.0 op_sel_hi:[1,0]
	v_pk_fma_f32 v[32:33], v[20:21], v[20:21], 1.0 op_sel_hi:[1,1,0] neg_lo:[1,0,0] neg_hi:[1,0,0]
	s_nop 0
	v_max_f32_e32 v33, 0, v33
	v_max_f32_e32 v32, 0, v32
	v_sqrt_f32_e32 v32, v32
	v_sqrt_f32_e32 v33, v33
	s_nop 0
	v_pk_mul_f32 v[32:33], v[34:35], v[32:33]
	s_nop 0
	v_pk_mul_f32 v[4:5], v[4:5], v[32:33]
	v_pk_add_f32 v[32:33], v[114:115], v[38:39]
	v_rcp_f32_e32 v34, v22
	v_pk_mul_f32 v[32:33], v[32:33], s[14:15] op_sel_hi:[1,0]
	v_rcp_f32_e32 v35, v23
	v_exp_f32_e32 v32, v32
	v_exp_f32_e32 v33, v33
	s_nop 0
	v_pk_add_f32 v[32:33], v[32:33], 1.0 op_sel_hi:[1,0]
	s_nop 0
	v_rcp_f32_e32 v32, v32
	v_rcp_f32_e32 v33, v33
	s_nop 0
	v_pk_mul_f32 v[22:23], v[118:119], v[32:33]
	s_nop 0
	v_exp_f32_e32 v22, v22
	v_exp_f32_e32 v23, v23
	s_nop 0
	v_pk_fma_f32 v[32:33], v[22:23], v[22:23], 1.0 op_sel_hi:[1,1,0] neg_lo:[1,0,0] neg_hi:[1,0,0]
	s_nop 0
	v_max_f32_e32 v33, 0, v33
	v_max_f32_e32 v32, 0, v32
	v_sqrt_f32_e32 v32, v32
	v_sqrt_f32_e32 v33, v33
	s_nop 0
	v_pk_mul_f32 v[32:33], v[34:35], v[32:33]
	s_nop 0
	v_pk_mul_f32 v[6:7], v[6:7], v[32:33]
	v_pk_add_f32 v[32:33], v[114:115], v[40:41]
	v_rcp_f32_e32 v34, v24
	v_pk_mul_f32 v[32:33], v[32:33], s[14:15] op_sel_hi:[1,0]
	v_rcp_f32_e32 v35, v25
	v_exp_f32_e32 v32, v32
	v_exp_f32_e32 v33, v33
	s_nop 0
	v_pk_add_f32 v[32:33], v[32:33], 1.0 op_sel_hi:[1,0]
	s_nop 0
	v_rcp_f32_e32 v32, v32
	v_rcp_f32_e32 v33, v33
	s_nop 0
	v_pk_mul_f32 v[24:25], v[118:119], v[32:33]
	s_nop 0
	v_exp_f32_e32 v24, v24
	v_exp_f32_e32 v25, v25
	s_nop 0
	v_pk_fma_f32 v[32:33], v[24:25], v[24:25], 1.0 op_sel_hi:[1,1,0] neg_lo:[1,0,0] neg_hi:[1,0,0]
	s_nop 0
	v_max_f32_e32 v33, 0, v33
	v_max_f32_e32 v32, 0, v32
	v_sqrt_f32_e32 v32, v32
	v_sqrt_f32_e32 v33, v33
	s_nop 0
	v_pk_mul_f32 v[32:33], v[34:35], v[32:33]
	s_nop 0
	v_pk_mul_f32 v[8:9], v[8:9], v[32:33]
	v_pk_add_f32 v[32:33], v[114:115], v[42:43]
	v_rcp_f32_e32 v34, v26
	v_pk_mul_f32 v[32:33], v[32:33], s[14:15] op_sel_hi:[1,0]
	v_rcp_f32_e32 v35, v27
	v_exp_f32_e32 v32, v32
	v_exp_f32_e32 v33, v33
	s_nop 0
	v_pk_add_f32 v[32:33], v[32:33], 1.0 op_sel_hi:[1,0]
	s_nop 0
	v_rcp_f32_e32 v32, v32
	v_rcp_f32_e32 v33, v33
	s_nop 0
	v_pk_mul_f32 v[26:27], v[118:119], v[32:33]
	s_nop 0
	v_exp_f32_e32 v26, v26
	v_exp_f32_e32 v27, v27
	s_nop 0
	v_pk_fma_f32 v[32:33], v[26:27], v[26:27], 1.0 op_sel_hi:[1,1,0] neg_lo:[1,0,0] neg_hi:[1,0,0]
	s_nop 0
	v_max_f32_e32 v33, 0, v33
	v_max_f32_e32 v32, 0, v32
	v_sqrt_f32_e32 v32, v32
	v_sqrt_f32_e32 v33, v33
	s_nop 0
	v_pk_mul_f32 v[32:33], v[34:35], v[32:33]
	s_nop 0
	v_pk_mul_f32 v[10:11], v[10:11], v[32:33]
	v_pk_add_f32 v[32:33], v[114:115], v[44:45]
	v_rcp_f32_e32 v34, v28
	v_pk_mul_f32 v[32:33], v[32:33], s[14:15] op_sel_hi:[1,0]
	v_rcp_f32_e32 v35, v29
	v_exp_f32_e32 v32, v32
	v_exp_f32_e32 v33, v33
	s_nop 0
	v_pk_add_f32 v[32:33], v[32:33], 1.0 op_sel_hi:[1,0]
	s_nop 0
	v_rcp_f32_e32 v32, v32
	v_rcp_f32_e32 v33, v33
	s_nop 0
	v_pk_mul_f32 v[28:29], v[118:119], v[32:33]
	s_nop 0
	v_exp_f32_e32 v28, v28
	v_exp_f32_e32 v29, v29
	s_nop 0
	v_pk_fma_f32 v[32:33], v[28:29], v[28:29], 1.0 op_sel_hi:[1,1,0] neg_lo:[1,0,0] neg_hi:[1,0,0]
	s_nop 0
	v_max_f32_e32 v33, 0, v33
	v_max_f32_e32 v32, 0, v32
	v_sqrt_f32_e32 v32, v32
	v_sqrt_f32_e32 v33, v33
	s_nop 0
	v_pk_mul_f32 v[32:33], v[34:35], v[32:33]
	s_nop 0
	v_pk_mul_f32 v[12:13], v[12:13], v[32:33]
	v_pk_add_f32 v[32:33], v[114:115], v[46:47]
	v_rcp_f32_e32 v34, v30
	v_pk_mul_f32 v[32:33], v[32:33], s[14:15] op_sel_hi:[1,0]
	v_rcp_f32_e32 v35, v31
	v_exp_f32_e32 v32, v32
	v_exp_f32_e32 v33, v33
	s_nop 0
	v_pk_add_f32 v[32:33], v[32:33], 1.0 op_sel_hi:[1,0]
	s_nop 0
	v_rcp_f32_e32 v32, v32
	v_rcp_f32_e32 v33, v33
	s_nop 0
	v_pk_mul_f32 v[30:31], v[118:119], v[32:33]
	s_nop 0
	v_exp_f32_e32 v30, v30
	v_exp_f32_e32 v31, v31
	s_nop 0
	v_pk_fma_f32 v[32:33], v[30:31], v[30:31], 1.0 op_sel_hi:[1,1,0] neg_lo:[1,0,0] neg_hi:[1,0,0]
	s_nop 0
	v_max_f32_e32 v33, 0, v33
	v_max_f32_e32 v32, 0, v32
	v_sqrt_f32_e32 v32, v32
	v_sqrt_f32_e32 v33, v33
	s_nop 0
	v_pk_mul_f32 v[32:33], v[34:35], v[32:33]
	s_nop 0
	v_pk_mul_f32 v[14:15], v[14:15], v[32:33]
	s_branch .LBB0_32

; __device__ __forceinline__ unsigned pk2(float lo, float hi) { unsigned r; asm("v_cvt_pk_bf16_f32 %0, %1, %2" : "=v"(r) : "v"(lo), "v"(hi)); return r; }
; template <int DIR>
; __device__ __forceinline__ void lru_dir(const bf16_t* XR, const bf16_t* GATE, bf16_t* YP, u32x4* HSF, const bf16_t* bdw_dir, float bias_r, float bias_i, float sp,
;                                         int b, int n2, int lane, int wave, LAS float* xl) {
;     ...
;         for (int k = 0; k < 2; ++k) {
;             const int q = seg * 16 + wave * 2 + k; valid[k] = q < 136;
;             const int T = DIR == 0 ? q : (q < 8 ? 7 - q : 143 - q);
;             trow[k] = T < 8 ? ML + b * CTXL + 32 * T : b * SEQ + 32 * (T - 8);
;             if (valid[k]) {
;                 const bf16_t* ap = XR + (size_t)(trow[k] + tau) * DM + n * 64 + 8 * hh;
;                 bf16x8 A[4];
; #pragma unroll
;                 for (int kk = 0; kk < 4; ++kk) A[kk] = *(const bf16x8*)(ap + 16 * kk);
;                 f32x16 ar, ai, xv;
; #pragma unroll
;                 for (int r = 0; r < 16; ++r) { ar[r] = 0.f; ai[r] = 0.f; xv[r] = 0.f; }
; #pragma unroll
;                 for (int kk = 0; kk < 4; ++kk) { ar = mfma32(A[kk], Br[kk], ar); ai = mfma32(A[kk], Bi[kk], ai); }
;                 const bf16x8 Ax0 = half ? A[2] : A[0], Ax1 = half ? A[3] : A[1];
;                 xv = mfma32(Ax0, I0, xv); xv = mfma32(Ax1, I1, xv);
;     ...
;                 const int tg = trow[k] < ML ? (trow[k] >> 12) * 136 + 8 + ((trow[k] & (SEQ - 1)) >> 5) : b * 136 + ((trow[k] - ML - b * CTXL) >> 5);
;                 u32x4* hp = HSF + (((size_t)tg * 32 + n2) * 64 + lane) * 2;
;                 if (DIR == 0) {
;                     u32x4 w0, w1;
;                     w0.x = pk2(hs[0], hs[1]); w0.y = pk2(hs[2], hs[3]); w0.z = pk2(hs[4], hs[5]); w0.w = pk2(hs[6], hs[7]);
;                     w1.x = pk2(hs[8], hs[9]); w1.y = pk2(hs[10], hs[11]); w1.z = pk2(hs[12], hs[13]); w1.w = pk2(hs[14], hs[15]);
;                     hp[0] = w0; hp[1] = w1;
;                 } else {
;                     const u32x4 w0 = hp[0], w1 = hp[1];
;                     const unsigned hw[8] = {w0.x, w0.y, w0.z, w0.w, w1.x, w1.y, w1.z, w1.w};
;                     const bf16_t* gp = GATE + (size_t)(trow[k] + tau) * DM + chcol + 8 * hh;
;                     const bf16x8 G0 = *(const bf16x8*)gp, G1 = *(const bf16x8*)(gp + 16);
.LBB0_48:
	s_cmpk_lt_i32 s35, 0x88
	s_cselect_b64 s[8:9], -1, 0
	s_cmp_gt_i32 s35, 7
	s_cselect_b32 s2, 0x8f, 7
	s_add_i32 s2, s2, s19
	s_lshl_b32 s3, s2, 5
	s_cmp_lt_i32 s2, 8
	s_cselect_b32 s36, s31, s29
	s_add_i32 s36, s36, s3
	v_or_b32_e32 v132, s36, v173
	s_cmpk_gt_i32 s35, 0x87
	v_mov_b32_e32 v126, 1.0
	v_ashrrev_i32_e32 v133, 31, v132
	v_mov_b32_e32 v138, 0
	v_mov_b32_e32 v139, 0
	v_mov_b32_e32 v134, 0
	v_mov_b32_e32 v135, 0
	v_mov_b32_e32 v136, 0
	v_mov_b32_e32 v137, 0
	v_mov_b32_e32 v128, 0
	v_mov_b32_e32 v129, 0
	v_mov_b32_e32 v130, 0
	v_mov_b32_e32 v131, 0
	v_mov_b32_e32 v146, 0
	v_mov_b32_e32 v147, 0
	v_mov_b32_e32 v148, 0
	v_mov_b32_e32 v149, 0
	v_mov_b32_e32 v150, 0
	v_mov_b32_e32 v151, 0
	v_mov_b32_e32 v140, 1.0
	v_mov_b32_e32 v141, 1.0
	v_mov_b32_e32 v152, 1.0
	v_mov_b32_e32 v153, 1.0
	v_mov_b32_e32 v156, 1.0
	v_mov_b32_e32 v157, 1.0
	v_mov_b32_e32 v158, 1.0
	v_mov_b32_e32 v159, 1.0
	v_mov_b32_e32 v162, 1.0
	v_mov_b32_e32 v163, 1.0
	v_mov_b32_e32 v164, 1.0
	v_mov_b32_e32 v165, 1.0
	v_mov_b32_e32 v166, 1.0
	v_mov_b32_e32 v167, 1.0
	v_mov_b32_e32 v168, 1.0
	v_mov_b32_e32 v169, 1.0
	s_cbranch_scc1 .LBB0_50
	v_lshlrev_b64 v[0:1], 11, v[132:133]
	v_lshl_add_u64 v[12:13], v[118:119], 0, v[0:1]
	s_mov_b32 s98, s36
	s_lshl_b32 s98, s98, 11
	s_add_u32 s98, s100, s98
	s_addc_u32 s99, s101, 0
	global_load_dwordx4 v[0:3], v234, s[98:99]
	global_load_dwordx4 v[4:7], v235, s[98:99]
	global_load_dwordx4 v[8:11], v236, s[98:99]
	global_load_dwordx4 v[12:15], v237, s[98:99]
	s_ashr_i32 s98, s36, 12
	s_mulk_i32 s98, 0x88
	s_bfe_u32 s99, s36, 0x70005
	s_add_i32 s98, s98, s99
	s_add_i32 s98, s98, 8
	s_sub_i32 s99, s36, s30
	s_addk_i32 s99, 0x8000
	s_ashr_i32 s99, s99, 5
	s_add_i32 s99, s99, s34
	s_cmp_lt_i32 s36, 0x8000
	s_cselect_b32 s98, s98, s99
	s_ashr_i32 s99, s98, 31
	s_lshl_b64 s[98:99], s[98:99], 16
	v_lshl_add_u64 v[216:217], v[112:113], 0, s[98:99]
	v_lshlrev_b64 v[218:219], 11, v[132:133]
	global_load_dwordx4 v[184:187], v[216:217], off offset:16
	global_load_dwordx4 v[188:191], v[216:217], off
	v_lshl_add_u64 v[218:219], v[120:121], 0, v[218:219]
	s_nop 0
	global_load_dwordx4 v[192:195], v[218:219], off
	global_load_dwordx4 v[196:199], v[218:219], off offset:32
	s_waitcnt vmcnt(7)
	ds_write_b128 v238, v[0:3]
	s_waitcnt vmcnt(6)
	ds_write_b128 v238, v[4:7] offset:1152
	s_waitcnt vmcnt(5)
	ds_write_b128 v238, v[8:11] offset:2304
	s_waitcnt vmcnt(4)
	ds_write_b128 v238, v[12:15] offset:3456
	ds_read_b128 v[0:3], v239
	ds_read_b128 v[4:7], v239 offset:32
	ds_read_b128 v[8:11], v239 offset:64
	ds_read_b128 v[12:15], v239 offset:96
	s_waitcnt lgkmcnt(0)
	v_mfma_f32_32x32x16_bf16 v[32:47], v[0:3], v[66:69], 0
	s_waitcnt vmcnt(4)
	v_cndmask_b32_e64 v131, v15, v7, s[56:57]
	v_cndmask_b32_e64 v130, v14, v6, s[56:57]
	v_cndmask_b32_e64 v129, v13, v5, s[56:57]
	v_cndmask_b32_e64 v128, v12, v4, s[56:57]
	v_mfma_f32_32x32x16_bf16 v[32:47], v[4:7], v[70:73], v[32:47]
	v_mfma_f32_32x32x16_bf16 v[16:31], v[0:3], v[82:85], 0
	v_cndmask_b32_e64 v3, v11, v3, s[56:57]
	v_cndmask_b32_e64 v2, v10, v2, s[56:57]
	v_cndmask_b32_e64 v1, v9, v1, s[56:57]
	v_cndmask_b32_e64 v0, v8, v0, s[56:57]
	v_mfma_f32_32x32x16_bf16 v[32:47], v[8:11], v[74:77], v[32:47]
	v_mfma_f32_32x32x16_bf16 v[16:31], v[4:7], v[86:89], v[16:31]
	v_mfma_f32_32x32x16_bf16 v[32:47], v[12:15], v[78:81], v[32:47]
	v_mfma_f32_32x32x16_bf16 v[16:31], v[8:11], v[90:93], v[16:31]
	s_nop 10
	v_add_f32_e64 v32, v114, v32
	v_add_f32_e64 v33, v115, v33
	v_mul_f32_e64 v32, v32, s14
	v_mul_f32_e64 v33, v33, s14
	v_exp_f32_e32 v32, v32
	v_exp_f32_e32 v33, v33
	v_mfma_f32_32x32x16_bf16 v[16:31], v[12:15], v[94:97], v[16:31]
	v_add_f32_e64 v32, v32, 1.0
	v_add_f32_e64 v33, v33, 1.0
	v_rcp_f32_e32 v32, v32
	v_rcp_f32_e32 v33, v33
	s_nop 0
	v_pk_mul_f32 v[32:33], v[124:125], v[32:33]
	v_mfma_f32_32x32x16_bf16 v[0:15], v[0:3], v[58:61], 0
	s_nop 4
	v_add_f32_e64 v16, v116, v16
	v_add_f32_e64 v17, v117, v17
	v_exp_f32_e32 v140, v32
	v_pk_mul_f32 v[16:17], v[16:17], s[14:15] op_sel_hi:[1,0]
	v_exp_f32_e32 v141, v33
	v_exp_f32_e32 v16, v16
	v_exp_f32_e32 v17, v17
	v_pk_fma_f32 v[32:33], v[140:141], v[140:141], 1.0 op_sel_hi:[1,1,0] neg_lo:[1,0,0] neg_hi:[1,0,0]
	v_mfma_f32_32x32x16_bf16 v[0:15], v[128:131], v[62:65], v[0:15]
	v_add_f32_e64 v16, v16, 1.0
	v_add_f32_e64 v17, v17, 1.0
	v_max_f32_e32 v33, 0, v33
	v_max_f32_e32 v32, 0, v32
	v_rcp_f32_e32 v16, v16
	v_rcp_f32_e32 v17, v17
	v_sqrt_f32_e32 v32, v32
	v_sqrt_f32_e32 v33, v33
	s_nop 0
	v_pk_mul_f32 v[16:17], v[16:17], v[32:33]
	s_nop 1
	v_pk_mul_f32 v[138:139], v[0:1], v[16:17]
	v_pk_add_f32 v[0:1], v[114:115], v[34:35]
	v_pk_add_f32 v[16:17], v[116:117], v[18:19]
	v_pk_mul_f32 v[0:1], v[0:1], s[14:15] op_sel_hi:[1,0]
	v_pk_mul_f32 v[16:17], v[16:17], s[14:15] op_sel_hi:[1,0]
	v_exp_f32_e32 v0, v0
	v_exp_f32_e32 v1, v1
	v_exp_f32_e32 v16, v16
	v_exp_f32_e32 v17, v17
	v_pk_add_f32 v[0:1], v[0:1], 1.0 op_sel_hi:[1,0]
	s_nop 0
	v_rcp_f32_e32 v0, v0
	v_rcp_f32_e32 v1, v1
	v_pk_add_f32 v[16:17], v[16:17], 1.0 op_sel_hi:[1,0]
	v_pk_mul_f32 v[0:1], v[124:125], v[0:1]
	s_nop 0
	v_exp_f32_e32 v152, v0
	v_exp_f32_e32 v153, v1
	v_rcp_f32_e32 v16, v16
	v_rcp_f32_e32 v17, v17
	v_pk_fma_f32 v[0:1], v[152:153], v[152:153], 1.0 op_sel_hi:[1,1,0] neg_lo:[1,0,0] neg_hi:[1,0,0]
	s_nop 0
	v_max_f32_e32 v1, 0, v1
	v_max_f32_e32 v0, 0, v0
	v_sqrt_f32_e32 v0, v0
	v_sqrt_f32_e32 v1, v1
	s_nop 0
	v_pk_mul_f32 v[0:1], v[16:17], v[0:1]
	s_nop 0
	v_pk_mul_f32 v[134:135], v[2:3], v[0:1]
	v_pk_add_f32 v[0:1], v[114:115], v[36:37]
	v_pk_add_f32 v[2:3], v[116:117], v[20:21]
	v_pk_mul_f32 v[0:1], v[0:1], s[14:15] op_sel_hi:[1,0]
	v_pk_mul_f32 v[2:3], v[2:3], s[14:15] op_sel_hi:[1,0]
; template <int DIR>
; __device__ __forceinline__ void lru_dir(const bf16_t* XR, const bf16_t* GATE, bf16_t* YP, u32x4* HSF, const bf16_t* bdw_dir, float bias_r, float bias_i, float sp,
;                                         int b, int n2, int lane, int wave, LAS float* xl) {
;     ...
;                 for (int r = 0; r < 16; r += 2) {
;                     const f32x2 er = ((f32x2){ar[r], ar[r + 1]} + bias_r) * -1.4426950408889634f, ei = ((f32x2){ai[r], ai[r + 1]} + bias_i) * -1.4426950408889634f;
;                     const f32x2 dr = (f32x2){__builtin_amdgcn_exp2f(er[0]), __builtin_amdgcn_exp2f(er[1])} + 1.0f, di = (f32x2){__builtin_amdgcn_exp2f(ei[0]), __builtin_amdgcn_exp2f(ei[1])} + 1.0f;
;                     const f32x2 rg = {__builtin_amdgcn_rcpf(dr[0]), __builtin_amdgcn_rcpf(dr[1])}, ig = {__builtin_amdgcn_rcpf(di[0]), __builtin_amdgcn_rcpf(di[1])};
;                     const f32x2 la = rg * spm;
;                     const f32x2 aa = {__builtin_amdgcn_exp2f(la[0]), __builtin_amdgcn_exp2f(la[1])};
;                     const f32x2 om = __builtin_elementwise_max(1.0f - aa * aa, (f32x2){0.f, 0.f});
;                     const f32x2 bb = (f32x2){__builtin_amdgcn_sqrtf(om[0]), __builtin_amdgcn_sqrtf(om[1])} * ig * (f32x2){xv[r], xv[r + 1]};
;                     av[k][r] = aa[0]; av[k][r + 1] = aa[1]; bv[k][r] = bb[0]; bv[k][r + 1] = bb[1];
;                 }
	v_exp_f32_e32 v0, v0
	v_exp_f32_e32 v1, v1
	v_exp_f32_e32 v2, v2
	v_exp_f32_e32 v3, v3
	v_pk_add_f32 v[0:1], v[0:1], 1.0 op_sel_hi:[1,0]
	s_nop 0
	v_rcp_f32_e32 v0, v0
	v_rcp_f32_e32 v1, v1
	v_pk_add_f32 v[2:3], v[2:3], 1.0 op_sel_hi:[1,0]
	v_pk_mul_f32 v[0:1], v[124:125], v[0:1]
	s_nop 0
	v_exp_f32_e32 v156, v0
	v_exp_f32_e32 v157, v1
	v_rcp_f32_e32 v2, v2
	v_rcp_f32_e32 v3, v3
	v_pk_fma_f32 v[0:1], v[156:157], v[156:157], 1.0 op_sel_hi:[1,1,0] neg_lo:[1,0,0] neg_hi:[1,0,0]
	s_nop 0
	v_max_f32_e32 v1, 0, v1
	v_max_f32_e32 v0, 0, v0
	v_sqrt_f32_e32 v0, v0
	v_sqrt_f32_e32 v1, v1
	s_nop 0
	v_pk_mul_f32 v[0:1], v[2:3], v[0:1]
	s_nop 0
	v_pk_mul_f32 v[136:137], v[4:5], v[0:1]
	v_pk_add_f32 v[0:1], v[114:115], v[38:39]
	v_pk_add_f32 v[2:3], v[116:117], v[22:23]
	v_pk_mul_f32 v[0:1], v[0:1], s[14:15] op_sel_hi:[1,0]
	v_pk_mul_f32 v[2:3], v[2:3], s[14:15] op_sel_hi:[1,0]
	v_exp_f32_e32 v0, v0
	v_exp_f32_e32 v1, v1
	v_exp_f32_e32 v2, v2
	v_exp_f32_e32 v3, v3
	v_pk_add_f32 v[0:1], v[0:1], 1.0 op_sel_hi:[1,0]
	s_nop 0
	v_rcp_f32_e32 v0, v0
	v_rcp_f32_e32 v1, v1
	v_pk_add_f32 v[2:3], v[2:3], 1.0 op_sel_hi:[1,0]
	v_pk_mul_f32 v[0:1], v[124:125], v[0:1]
	s_nop 0
	v_exp_f32_e32 v158, v0
	v_exp_f32_e32 v159, v1
	v_rcp_f32_e32 v2, v2
	v_rcp_f32_e32 v3, v3
	v_pk_fma_f32 v[0:1], v[158:159], v[158:159], 1.0 op_sel_hi:[1,1,0] neg_lo:[1,0,0] neg_hi:[1,0,0]
	s_nop 0
	v_max_f32_e32 v1, 0, v1
	v_max_f32_e32 v0, 0, v0
	v_sqrt_f32_e32 v0, v0
	v_sqrt_f32_e32 v1, v1
	s_nop 0
	v_pk_mul_f32 v[0:1], v[2:3], v[0:1]
	s_nop 0
	v_pk_mul_f32 v[128:129], v[6:7], v[0:1]
	v_pk_add_f32 v[0:1], v[114:115], v[40:41]
	v_pk_add_f32 v[2:3], v[116:117], v[24:25]
	v_pk_mul_f32 v[0:1], v[0:1], s[14:15] op_sel_hi:[1,0]
	v_pk_mul_f32 v[2:3], v[2:3], s[14:15] op_sel_hi:[1,0]
	v_exp_f32_e32 v0, v0
	v_exp_f32_e32 v1, v1
	v_exp_f32_e32 v2, v2
	v_exp_f32_e32 v3, v3
	v_pk_add_f32 v[0:1], v[0:1], 1.0 op_sel_hi:[1,0]
	s_nop 0
	v_rcp_f32_e32 v0, v0
	v_rcp_f32_e32 v1, v1
	v_pk_add_f32 v[2:3], v[2:3], 1.0 op_sel_hi:[1,0]
	v_pk_mul_f32 v[0:1], v[124:125], v[0:1]
	s_nop 0
	v_exp_f32_e32 v162, v0
	v_exp_f32_e32 v163, v1
	v_rcp_f32_e32 v2, v2
	v_rcp_f32_e32 v3, v3
	v_pk_fma_f32 v[0:1], v[162:163], v[162:163], 1.0 op_sel_hi:[1,1,0] neg_lo:[1,0,0] neg_hi:[1,0,0]
	s_nop 0
	v_max_f32_e32 v1, 0, v1
	v_max_f32_e32 v0, 0, v0
	v_sqrt_f32_e32 v0, v0
	v_sqrt_f32_e32 v1, v1
	s_nop 0
	v_pk_mul_f32 v[0:1], v[2:3], v[0:1]
	s_nop 0
	v_pk_mul_f32 v[130:131], v[8:9], v[0:1]
	v_pk_add_f32 v[0:1], v[114:115], v[42:43]
	v_pk_add_f32 v[2:3], v[116:117], v[26:27]
	v_pk_mul_f32 v[0:1], v[0:1], s[14:15] op_sel_hi:[1,0]
	v_pk_mul_f32 v[2:3], v[2:3], s[14:15] op_sel_hi:[1,0]
	v_exp_f32_e32 v0, v0
	v_exp_f32_e32 v1, v1
	v_exp_f32_e32 v2, v2
	v_exp_f32_e32 v3, v3
	v_pk_add_f32 v[0:1], v[0:1], 1.0 op_sel_hi:[1,0]
	s_nop 0
	v_rcp_f32_e32 v0, v0
	v_rcp_f32_e32 v1, v1
	v_pk_add_f32 v[2:3], v[2:3], 1.0 op_sel_hi:[1,0]
	v_pk_mul_f32 v[0:1], v[124:125], v[0:1]
	s_nop 0
	v_exp_f32_e32 v164, v0
	v_exp_f32_e32 v165, v1
	v_rcp_f32_e32 v2, v2
	v_rcp_f32_e32 v3, v3
	v_pk_fma_f32 v[0:1], v[164:165], v[164:165], 1.0 op_sel_hi:[1,1,0] neg_lo:[1,0,0] neg_hi:[1,0,0]
	s_nop 0
	v_max_f32_e32 v1, 0, v1
	v_max_f32_e32 v0, 0, v0
	v_sqrt_f32_e32 v0, v0
	v_sqrt_f32_e32 v1, v1
	s_nop 0
	v_pk_mul_f32 v[0:1], v[2:3], v[0:1]
	s_nop 0
	v_pk_mul_f32 v[146:147], v[10:11], v[0:1]
	v_pk_add_f32 v[0:1], v[114:115], v[44:45]
	v_pk_add_f32 v[2:3], v[116:117], v[28:29]
	v_pk_mul_f32 v[0:1], v[0:1], s[14:15] op_sel_hi:[1,0]
	v_pk_mul_f32 v[2:3], v[2:3], s[14:15] op_sel_hi:[1,0]
	v_exp_f32_e32 v0, v0
	v_exp_f32_e32 v1, v1
	v_exp_f32_e32 v2, v2
	v_exp_f32_e32 v3, v3
	v_pk_add_f32 v[0:1], v[0:1], 1.0 op_sel_hi:[1,0]
	s_nop 0
	v_rcp_f32_e32 v0, v0
	v_rcp_f32_e32 v1, v1
	v_pk_add_f32 v[2:3], v[2:3], 1.0 op_sel_hi:[1,0]
	v_pk_mul_f32 v[0:1], v[124:125], v[0:1]
	s_nop 0
	v_exp_f32_e32 v166, v0
	v_exp_f32_e32 v167, v1
	v_rcp_f32_e32 v2, v2
	v_rcp_f32_e32 v3, v3
	v_pk_fma_f32 v[0:1], v[166:167], v[166:167], 1.0 op_sel_hi:[1,1,0] neg_lo:[1,0,0] neg_hi:[1,0,0]
	s_nop 0
	v_max_f32_e32 v1, 0, v1
	v_max_f32_e32 v0, 0, v0
	v_sqrt_f32_e32 v0, v0
	v_sqrt_f32_e32 v1, v1
	s_nop 0
	v_pk_mul_f32 v[0:1], v[2:3], v[0:1]
	s_nop 0
	v_pk_mul_f32 v[148:149], v[12:13], v[0:1]
	v_pk_add_f32 v[0:1], v[114:115], v[46:47]
	v_pk_add_f32 v[2:3], v[116:117], v[30:31]
	v_pk_mul_f32 v[0:1], v[0:1], s[14:15] op_sel_hi:[1,0]
	v_pk_mul_f32 v[2:3], v[2:3], s[14:15] op_sel_hi:[1,0]
	v_exp_f32_e32 v0, v0
	v_exp_f32_e32 v1, v1
	v_exp_f32_e32 v2, v2
	v_exp_f32_e32 v3, v3
	v_pk_add_f32 v[0:1], v[0:1], 1.0 op_sel_hi:[1,0]
	s_nop 0
	v_rcp_f32_e32 v0, v0
	v_rcp_f32_e32 v1, v1
	v_pk_add_f32 v[2:3], v[2:3], 1.0 op_sel_hi:[1,0]
	v_pk_mul_f32 v[0:1], v[124:125], v[0:1]
	s_nop 0
	v_exp_f32_e32 v168, v0
	v_exp_f32_e32 v169, v1
	v_rcp_f32_e32 v2, v2
	v_rcp_f32_e32 v3, v3
	v_pk_fma_f32 v[0:1], v[168:169], v[168:169], 1.0 op_sel_hi:[1,1,0] neg_lo:[1,0,0] neg_hi:[1,0,0]
	s_nop 0
	v_max_f32_e32 v1, 0, v1
	v_max_f32_e32 v0, 0, v0
	v_sqrt_f32_e32 v0, v0
	v_sqrt_f32_e32 v1, v1
	s_nop 0
	v_pk_mul_f32 v[0:1], v[2:3], v[0:1]
	s_nop 0
	v_pk_mul_f32 v[150:151], v[14:15], v[0:1]
; __device__ __forceinline__ f32x16 mfma32(bf16x8 a, bf16x8 b, f32x16 c) { return __builtin_amdgcn_mfma_f32_32x32x16_bf16(a, b, c, 0, 0, 0); }
; template <int DIR>
; __device__ __forceinline__ void lru_dir(const bf16_t* XR, const bf16_t* GATE, bf16_t* YP, u32x4* HSF, const bf16_t* bdw_dir, float bias_r, float bias_i, float sp,
;                                         int b, int n2, int lane, int wave, LAS float* xl) {
;     ...
;         for (int k = 0; k < 2; ++k) {
;             const int q = seg * 16 + wave * 2 + k; valid[k] = q < 136;
;             const int T = DIR == 0 ? q : (q < 8 ? 7 - q : 143 - q);
;             trow[k] = T < 8 ? ML + b * CTXL + 32 * T : b * SEQ + 32 * (T - 8);
;             if (valid[k]) {
;                 const bf16_t* ap = XR + (size_t)(trow[k] + tau) * DM + n * 64 + 8 * hh;
;                 bf16x8 A[4];
; #pragma unroll
;                 for (int kk = 0; kk < 4; ++kk) A[kk] = *(const bf16x8*)(ap + 16 * kk);
;                 f32x16 ar, ai, xv;
; #pragma unroll
;                 for (int r = 0; r < 16; ++r) { ar[r] = 0.f; ai[r] = 0.f; xv[r] = 0.f; }
; #pragma unroll
;                 for (int kk = 0; kk < 4; ++kk) { ar = mfma32(A[kk], Br[kk], ar); ai = mfma32(A[kk], Bi[kk], ai); }
;                 const bf16x8 Ax0 = half ? A[2] : A[0], Ax1 = half ? A[3] : A[1];
;                 xv = mfma32(Ax0, I0, xv); xv = mfma32(Ax1, I1, xv);
;     ...
;             float H = 0.f, P = 1.f;
; #pragma unroll
;             for (int rr = 0; rr < 16; ++rr) { const int r = DIR == 0 ? rr : 15 - rr; H = av[k][r] * H + bv[k][r]; P *= av[k][r]; }
;             Hl[k] = H; Pl[k] = P;
;             const float val = H + P * hloc, got = __shfl_xor(val, 32);
;             const float st2 = first ? hloc : got;
;             const float endv = H + P * st2, got2 = __shfl_xor(endv, 32);
;             hloc = first ? got2 : endv;
;             ploc *= P * __shfl_xor(P, 32);
.LBB0_50:
	s_nop 0
	v_fma_f32 v0, 0, v169, v151
	v_fma_f32 v0, v168, v0, v150
	v_mul_f32_e32 v1, v169, v168
	v_fma_f32 v0, v167, v0, v149
	v_mul_f32_e32 v1, v167, v1
	v_fma_f32 v0, v166, v0, v148
	v_mul_f32_e32 v1, v166, v1
	v_fma_f32 v0, v165, v0, v147
	v_mul_f32_e32 v1, v165, v1
	v_fma_f32 v0, v164, v0, v146
	v_mul_f32_e32 v1, v164, v1
	v_fma_f32 v0, v163, v0, v131
	v_mul_f32_e32 v1, v163, v1
	v_fma_f32 v0, v162, v0, v130
	v_mul_f32_e32 v1, v162, v1
	v_fma_f32 v0, v159, v0, v129
	v_mul_f32_e32 v1, v159, v1
	v_fma_f32 v0, v158, v0, v128
	v_mul_f32_e32 v1, v158, v1
	v_fma_f32 v0, v157, v0, v137
	v_mul_f32_e32 v1, v157, v1
	v_fma_f32 v0, v156, v0, v136
	v_mul_f32_e32 v1, v156, v1
	v_fma_f32 v0, v153, v0, v135
	v_mul_f32_e32 v1, v153, v1
	v_fma_f32 v0, v152, v0, v134
	v_mul_f32_e32 v1, v152, v1
	v_fma_f32 v0, v141, v0, v139
	v_mul_f32_e32 v1, v141, v1
	v_fma_f32 v111, v140, v0, v138
	v_mul_f32_e32 v175, v140, v1
	v_fma_f32 v0, 0, v175, v111
	ds_bpermute_b32 v0, v176, v0
	s_add_i32 s2, s35, 1
	s_cmpk_lt_i32 s2, 0x88
	s_cselect_b64 s[10:11], -1, 0
	s_cmp_lt_i32 s35, 7
	s_cselect_b32 s3, 7, 0x8f
	s_add_i32 s3, s3, s19
	s_waitcnt lgkmcnt(0)
	v_cndmask_b32_e64 v0, 0, v0, s[40:41]
	s_add_i32 s3, s3, -1
	v_fma_f32 v48, v0, v175, v111
	s_lshl_b32 s6, s3, 5
	ds_bpermute_b32 v99, v176, v48
	ds_bpermute_b32 v98, v176, v175
	s_cmp_lt_i32 s3, 8
	s_cselect_b32 s37, s31, s29
	s_add_i32 s37, s37, s6
	v_or_b32_e32 v144, s37, v173
	v_mov_b32_e32 v154, 0
	s_cmpk_gt_i32 s2, 0x87
	v_ashrrev_i32_e32 v145, 31, v144
	v_mov_b32_e32 v155, 0
	v_mov_b32_e32 v142, 0
	v_mov_b32_e32 v143, 0
	v_mov_b32_e32 v34, 0
	v_mov_b32_e32 v35, 0
	v_mov_b32_e32 v32, 0
	v_mov_b32_e32 v33, 0
	v_mov_b32_e32 v24, 0
	v_mov_b32_e32 v25, 0
	v_mov_b32_e32 v26, 0
	v_mov_b32_e32 v27, 0
	v_mov_b32_e32 v28, 0
	v_mov_b32_e32 v29, 0
	v_mov_b32_e32 v30, 0
	v_mov_b32_e32 v31, 0
	v_mov_b32_e32 v127, 1.0
	v_mov_b32_e32 v160, 1.0
	v_mov_b32_e32 v161, 1.0
	v_mov_b32_e32 v36, 1.0
	v_mov_b32_e32 v37, 1.0
	v_mov_b32_e32 v38, 1.0
	v_mov_b32_e32 v39, 1.0
	v_mov_b32_e32 v40, 1.0
	v_mov_b32_e32 v41, 1.0
	v_mov_b32_e32 v42, 1.0
	v_mov_b32_e32 v43, 1.0
	v_mov_b32_e32 v44, 1.0
	v_mov_b32_e32 v45, 1.0
	v_mov_b32_e32 v46, 1.0
	v_mov_b32_e32 v47, 1.0
	s_cbranch_scc1 .LBB0_52
	v_lshlrev_b64 v[0:1], 11, v[144:145]
	v_lshl_add_u64 v[12:13], v[118:119], 0, v[0:1]
	s_mov_b32 s98, s37
	s_lshl_b32 s98, s98, 11
	s_add_u32 s98, s100, s98
	s_addc_u32 s99, s101, 0
	global_load_dwordx4 v[0:3], v234, s[98:99]
	global_load_dwordx4 v[4:7], v235, s[98:99]
	global_load_dwordx4 v[8:11], v236, s[98:99]
	global_load_dwordx4 v[12:15], v237, s[98:99]
	s_ashr_i32 s98, s37, 12
	s_mulk_i32 s98, 0x88
	s_lshr_b32 s99, s37, 5
	s_and_b32 s99, s99, 0x7e
	s_add_i32 s98, s98, s99
	s_add_i32 s98, s98, 8
	s_sub_i32 s99, s37, s30
	s_addk_i32 s99, 0x8000
	s_ashr_i32 s99, s99, 5
	s_add_i32 s99, s99, s34
	s_cmp_lt_i32 s37, 0x8000
	s_cselect_b32 s98, s98, s99
	s_ashr_i32 s99, s98, 31
	s_lshl_b64 s[98:99], s[98:99], 16
	v_lshl_add_u64 v[216:217], v[112:113], 0, s[98:99]
	v_lshlrev_b64 v[218:219], 11, v[144:145]
	global_load_dwordx4 v[200:203], v[216:217], off offset:16
	global_load_dwordx4 v[204:207], v[216:217], off
	v_lshl_add_u64 v[218:219], v[120:121], 0, v[218:219]
	s_nop 0
	global_load_dwordx4 v[208:211], v[218:219], off
	global_load_dwordx4 v[212:215], v[218:219], off offset:32
	s_waitcnt vmcnt(7)
	ds_write_b128 v238, v[0:3]
	s_waitcnt vmcnt(6)
	ds_write_b128 v238, v[4:7] offset:1152
	s_waitcnt vmcnt(5)
	ds_write_b128 v238, v[8:11] offset:2304
	s_waitcnt vmcnt(4)
	ds_write_b128 v238, v[12:15] offset:3456
	ds_read_b128 v[0:3], v239
	ds_read_b128 v[4:7], v239 offset:32
	ds_read_b128 v[8:11], v239 offset:64
	ds_read_b128 v[12:15], v239 offset:96
	s_waitcnt lgkmcnt(0)
	v_mfma_f32_32x32x16_bf16 v[32:47], v[0:3], v[66:69], 0
	s_waitcnt vmcnt(4)
	v_cndmask_b32_e64 v183, v15, v7, s[56:57]
	v_cndmask_b32_e64 v182, v14, v6, s[56:57]
	v_cndmask_b32_e64 v181, v13, v5, s[56:57]
	v_cndmask_b32_e64 v180, v12, v4, s[56:57]
	v_mfma_f32_32x32x16_bf16 v[32:47], v[4:7], v[70:73], v[32:47]
	v_mfma_f32_32x32x16_bf16 v[16:31], v[0:3], v[82:85], 0
	v_cndmask_b32_e64 v3, v11, v3, s[56:57]
	v_cndmask_b32_e64 v2, v10, v2, s[56:57]
	v_cndmask_b32_e64 v1, v9, v1, s[56:57]
	v_cndmask_b32_e64 v0, v8, v0, s[56:57]
	v_mfma_f32_32x32x16_bf16 v[32:47], v[8:11], v[74:77], v[32:47]
	v_mfma_f32_32x32x16_bf16 v[16:31], v[4:7], v[86:89], v[16:31]
	v_mfma_f32_32x32x16_bf16 v[32:47], v[12:15], v[78:81], v[32:47]
	v_mfma_f32_32x32x16_bf16 v[16:31], v[8:11], v[90:93], v[16:31]
	s_nop 10
	v_add_f32_e64 v32, v114, v32
	v_add_f32_e64 v33, v115, v33
	v_mul_f32_e64 v32, v32, s14
	v_mul_f32_e64 v33, v33, s14
	v_exp_f32_e32 v32, v32
	v_exp_f32_e32 v33, v33
	v_mfma_f32_32x32x16_bf16 v[16:31], v[12:15], v[94:97], v[16:31]
	v_add_f32_e64 v32, v32, 1.0
	v_add_f32_e64 v33, v33, 1.0
	v_rcp_f32_e32 v32, v32
	v_rcp_f32_e32 v33, v33
	s_nop 0
	v_pk_mul_f32 v[32:33], v[124:125], v[32:33]
	v_mfma_f32_32x32x16_bf16 v[0:15], v[0:3], v[58:61], 0
	s_nop 4
	v_add_f32_e64 v16, v116, v16
	v_add_f32_e64 v17, v117, v17
	v_exp_f32_e32 v126, v32
	v_pk_mul_f32 v[16:17], v[16:17], s[14:15] op_sel_hi:[1,0]
	v_exp_f32_e32 v127, v33
	v_exp_f32_e32 v16, v16
	v_exp_f32_e32 v17, v17
	v_pk_fma_f32 v[32:33], v[126:127], v[126:127], 1.0 op_sel_hi:[1,1,0] neg_lo:[1,0,0] neg_hi:[1,0,0]
	v_mfma_f32_32x32x16_bf16 v[0:15], v[180:183], v[62:65], v[0:15]
	v_add_f32_e64 v16, v16, 1.0
	v_add_f32_e64 v17, v17, 1.0
	v_max_f32_e32 v33, 0, v33
	v_max_f32_e32 v32, 0, v32
	v_rcp_f32_e32 v16, v16
	v_rcp_f32_e32 v17, v17
	v_sqrt_f32_e32 v32, v32
	v_sqrt_f32_e32 v33, v33
	s_nop 0
	v_pk_mul_f32 v[16:17], v[16:17], v[32:33]
	s_nop 1
; template <int DIR>
; __device__ __forceinline__ void lru_dir(const bf16_t* XR, const bf16_t* GATE, bf16_t* YP, u32x4* HSF, const bf16_t* bdw_dir, float bias_r, float bias_i, float sp,
;                                         int b, int n2, int lane, int wave, LAS float* xl) {
;     ...
;                 for (int r = 0; r < 16; r += 2) {
;                     const f32x2 er = ((f32x2){ar[r], ar[r + 1]} + bias_r) * -1.4426950408889634f, ei = ((f32x2){ai[r], ai[r + 1]} + bias_i) * -1.4426950408889634f;
;                     const f32x2 dr = (f32x2){__builtin_amdgcn_exp2f(er[0]), __builtin_amdgcn_exp2f(er[1])} + 1.0f, di = (f32x2){__builtin_amdgcn_exp2f(ei[0]), __builtin_amdgcn_exp2f(ei[1])} + 1.0f;
;                     const f32x2 rg = {__builtin_amdgcn_rcpf(dr[0]), __builtin_amdgcn_rcpf(dr[1])}, ig = {__builtin_amdgcn_rcpf(di[0]), __builtin_amdgcn_rcpf(di[1])};
;                     const f32x2 la = rg * spm;
;                     const f32x2 aa = {__builtin_amdgcn_exp2f(la[0]), __builtin_amdgcn_exp2f(la[1])};
;                     const f32x2 om = __builtin_elementwise_max(1.0f - aa * aa, (f32x2){0.f, 0.f});
;                     const f32x2 bb = (f32x2){__builtin_amdgcn_sqrtf(om[0]), __builtin_amdgcn_sqrtf(om[1])} * ig * (f32x2){xv[r], xv[r + 1]};
;                     av[k][r] = aa[0]; av[k][r + 1] = aa[1]; bv[k][r] = bb[0]; bv[k][r + 1] = bb[1];
;                 }
	v_pk_mul_f32 v[154:155], v[0:1], v[16:17]
	v_pk_add_f32 v[0:1], v[114:115], v[34:35]
	v_pk_add_f32 v[16:17], v[116:117], v[18:19]
	v_pk_mul_f32 v[0:1], v[0:1], s[14:15] op_sel_hi:[1,0]
	v_pk_mul_f32 v[16:17], v[16:17], s[14:15] op_sel_hi:[1,0]
	v_exp_f32_e32 v0, v0
	v_exp_f32_e32 v1, v1
	v_exp_f32_e32 v16, v16
	v_exp_f32_e32 v17, v17
	v_pk_add_f32 v[0:1], v[0:1], 1.0 op_sel_hi:[1,0]
	s_nop 0
	v_rcp_f32_e32 v0, v0
	v_rcp_f32_e32 v1, v1
	v_pk_add_f32 v[16:17], v[16:17], 1.0 op_sel_hi:[1,0]
	v_pk_mul_f32 v[0:1], v[124:125], v[0:1]
	s_nop 0
	v_exp_f32_e32 v160, v0
	v_exp_f32_e32 v161, v1
	v_rcp_f32_e32 v16, v16
	v_rcp_f32_e32 v17, v17
	v_pk_fma_f32 v[0:1], v[160:161], v[160:161], 1.0 op_sel_hi:[1,1,0] neg_lo:[1,0,0] neg_hi:[1,0,0]
	s_nop 0
	v_max_f32_e32 v1, 0, v1
	v_max_f32_e32 v0, 0, v0
	v_sqrt_f32_e32 v0, v0
	v_sqrt_f32_e32 v1, v1
	s_nop 0
	v_pk_mul_f32 v[0:1], v[16:17], v[0:1]
	s_nop 0
	v_pk_mul_f32 v[142:143], v[2:3], v[0:1]
	v_pk_add_f32 v[0:1], v[114:115], v[36:37]
	v_pk_add_f32 v[2:3], v[116:117], v[20:21]
	v_pk_mul_f32 v[0:1], v[0:1], s[14:15] op_sel_hi:[1,0]
	v_pk_mul_f32 v[2:3], v[2:3], s[14:15] op_sel_hi:[1,0]
	v_exp_f32_e32 v0, v0
	v_exp_f32_e32 v1, v1
	v_exp_f32_e32 v2, v2
	v_exp_f32_e32 v3, v3
	v_pk_add_f32 v[0:1], v[0:1], 1.0 op_sel_hi:[1,0]
	s_nop 0
	v_rcp_f32_e32 v0, v0
	v_rcp_f32_e32 v1, v1
	v_pk_add_f32 v[2:3], v[2:3], 1.0 op_sel_hi:[1,0]
	v_pk_mul_f32 v[0:1], v[124:125], v[0:1]
	s_nop 0
	v_exp_f32_e32 v36, v0
	v_exp_f32_e32 v37, v1
	v_rcp_f32_e32 v2, v2
	v_rcp_f32_e32 v3, v3
	v_pk_fma_f32 v[0:1], v[36:37], v[36:37], 1.0 op_sel_hi:[1,1,0] neg_lo:[1,0,0] neg_hi:[1,0,0]
	s_nop 0
	v_max_f32_e32 v1, 0, v1
	v_max_f32_e32 v0, 0, v0
	v_sqrt_f32_e32 v0, v0
	v_sqrt_f32_e32 v1, v1
	s_nop 0
	v_pk_mul_f32 v[0:1], v[2:3], v[0:1]
	s_nop 0
	v_pk_mul_f32 v[34:35], v[4:5], v[0:1]
	v_pk_add_f32 v[0:1], v[114:115], v[38:39]
	v_pk_add_f32 v[2:3], v[116:117], v[22:23]
	v_pk_mul_f32 v[0:1], v[0:1], s[14:15] op_sel_hi:[1,0]
	v_pk_mul_f32 v[2:3], v[2:3], s[14:15] op_sel_hi:[1,0]
	v_exp_f32_e32 v0, v0
	v_exp_f32_e32 v1, v1
	v_exp_f32_e32 v2, v2
	v_exp_f32_e32 v3, v3
	v_pk_add_f32 v[0:1], v[0:1], 1.0 op_sel_hi:[1,0]
	s_nop 0
	v_rcp_f32_e32 v0, v0
	v_rcp_f32_e32 v1, v1
	v_pk_add_f32 v[2:3], v[2:3], 1.0 op_sel_hi:[1,0]
	v_pk_mul_f32 v[0:1], v[124:125], v[0:1]
	s_nop 0
	v_exp_f32_e32 v38, v0
	v_exp_f32_e32 v39, v1
	v_rcp_f32_e32 v2, v2
	v_rcp_f32_e32 v3, v3
	v_pk_fma_f32 v[0:1], v[38:39], v[38:39], 1.0 op_sel_hi:[1,1,0] neg_lo:[1,0,0] neg_hi:[1,0,0]
	s_nop 0
	v_max_f32_e32 v1, 0, v1
	v_max_f32_e32 v0, 0, v0
	v_sqrt_f32_e32 v0, v0
	v_sqrt_f32_e32 v1, v1
	s_nop 0
	v_pk_mul_f32 v[0:1], v[2:3], v[0:1]
	s_nop 0
	v_pk_mul_f32 v[32:33], v[6:7], v[0:1]
	v_pk_add_f32 v[0:1], v[114:115], v[40:41]
	v_pk_add_f32 v[2:3], v[116:117], v[24:25]
	v_pk_mul_f32 v[0:1], v[0:1], s[14:15] op_sel_hi:[1,0]
	v_pk_mul_f32 v[2:3], v[2:3], s[14:15] op_sel_hi:[1,0]
	v_exp_f32_e32 v0, v0
	v_exp_f32_e32 v1, v1
	v_exp_f32_e32 v2, v2
	v_exp_f32_e32 v3, v3
	v_pk_add_f32 v[0:1], v[0:1], 1.0 op_sel_hi:[1,0]
	s_nop 0
	v_rcp_f32_e32 v0, v0
	v_rcp_f32_e32 v1, v1
	v_pk_add_f32 v[2:3], v[2:3], 1.0 op_sel_hi:[1,0]
	v_pk_mul_f32 v[0:1], v[124:125], v[0:1]
	s_nop 0
	v_exp_f32_e32 v40, v0
	v_exp_f32_e32 v41, v1
	v_rcp_f32_e32 v2, v2
	v_rcp_f32_e32 v3, v3
	v_pk_fma_f32 v[0:1], v[40:41], v[40:41], 1.0 op_sel_hi:[1,1,0] neg_lo:[1,0,0] neg_hi:[1,0,0]
	s_nop 0
	v_max_f32_e32 v1, 0, v1
	v_max_f32_e32 v0, 0, v0
	v_sqrt_f32_e32 v0, v0
	v_sqrt_f32_e32 v1, v1
	s_nop 0
	v_pk_mul_f32 v[0:1], v[2:3], v[0:1]
	s_nop 0
	v_pk_mul_f32 v[24:25], v[8:9], v[0:1]
	v_pk_add_f32 v[0:1], v[114:115], v[42:43]
	v_pk_add_f32 v[2:3], v[116:117], v[26:27]
	v_pk_mul_f32 v[0:1], v[0:1], s[14:15] op_sel_hi:[1,0]
	v_pk_mul_f32 v[2:3], v[2:3], s[14:15] op_sel_hi:[1,0]
	v_exp_f32_e32 v0, v0
	v_exp_f32_e32 v1, v1
	v_exp_f32_e32 v2, v2
	v_exp_f32_e32 v3, v3
	v_pk_add_f32 v[0:1], v[0:1], 1.0 op_sel_hi:[1,0]
	s_nop 0
	v_rcp_f32_e32 v0, v0
	v_rcp_f32_e32 v1, v1
	v_pk_add_f32 v[2:3], v[2:3], 1.0 op_sel_hi:[1,0]
	v_pk_mul_f32 v[0:1], v[124:125], v[0:1]
	s_nop 0
	v_exp_f32_e32 v42, v0
	v_exp_f32_e32 v43, v1
	v_rcp_f32_e32 v2, v2
	v_rcp_f32_e32 v3, v3
	v_pk_fma_f32 v[0:1], v[42:43], v[42:43], 1.0 op_sel_hi:[1,1,0] neg_lo:[1,0,0] neg_hi:[1,0,0]
	s_nop 0
	v_max_f32_e32 v1, 0, v1
	v_max_f32_e32 v0, 0, v0
	v_sqrt_f32_e32 v0, v0
	v_sqrt_f32_e32 v1, v1
	s_nop 0
	v_pk_mul_f32 v[0:1], v[2:3], v[0:1]
	s_nop 0
	v_pk_mul_f32 v[26:27], v[10:11], v[0:1]
	v_pk_add_f32 v[0:1], v[114:115], v[44:45]
	v_pk_add_f32 v[2:3], v[116:117], v[28:29]
	v_pk_mul_f32 v[0:1], v[0:1], s[14:15] op_sel_hi:[1,0]
	v_pk_mul_f32 v[2:3], v[2:3], s[14:15] op_sel_hi:[1,0]
	v_exp_f32_e32 v0, v0
	v_exp_f32_e32 v1, v1
	v_exp_f32_e32 v2, v2
	v_exp_f32_e32 v3, v3
	v_pk_add_f32 v[0:1], v[0:1], 1.0 op_sel_hi:[1,0]
	s_nop 0
	v_rcp_f32_e32 v0, v0
	v_rcp_f32_e32 v1, v1
	v_pk_add_f32 v[2:3], v[2:3], 1.0 op_sel_hi:[1,0]
	v_pk_mul_f32 v[0:1], v[124:125], v[0:1]
	s_nop 0
	v_exp_f32_e32 v44, v0
	v_exp_f32_e32 v45, v1
	v_rcp_f32_e32 v2, v2
	v_rcp_f32_e32 v3, v3
	v_pk_fma_f32 v[0:1], v[44:45], v[44:45], 1.0 op_sel_hi:[1,1,0] neg_lo:[1,0,0] neg_hi:[1,0,0]
	s_nop 0
	v_max_f32_e32 v1, 0, v1
	v_max_f32_e32 v0, 0, v0
	v_sqrt_f32_e32 v0, v0
	v_sqrt_f32_e32 v1, v1
	s_nop 0
	v_pk_mul_f32 v[0:1], v[2:3], v[0:1]
	s_nop 0
	v_pk_mul_f32 v[28:29], v[12:13], v[0:1]
	v_pk_add_f32 v[0:1], v[114:115], v[46:47]
	v_pk_add_f32 v[2:3], v[116:117], v[30:31]
	v_pk_mul_f32 v[0:1], v[0:1], s[14:15] op_sel_hi:[1,0]
	v_pk_mul_f32 v[2:3], v[2:3], s[14:15] op_sel_hi:[1,0]
	v_exp_f32_e32 v0, v0
	v_exp_f32_e32 v1, v1
	v_exp_f32_e32 v2, v2
	v_exp_f32_e32 v3, v3
	v_pk_add_f32 v[0:1], v[0:1], 1.0 op_sel_hi:[1,0]
	s_nop 0
	v_rcp_f32_e32 v0, v0
	v_rcp_f32_e32 v1, v1
	v_pk_add_f32 v[2:3], v[2:3], 1.0 op_sel_hi:[1,0]
	v_pk_mul_f32 v[0:1], v[124:125], v[0:1]
	s_nop 0
	v_exp_f32_e32 v46, v0
	v_exp_f32_e32 v47, v1
	v_rcp_f32_e32 v2, v2
	v_rcp_f32_e32 v3, v3
	v_pk_fma_f32 v[0:1], v[46:47], v[46:47], 1.0 op_sel_hi:[1,1,0] neg_lo:[1,0,0] neg_hi:[1,0,0]
	s_nop 0
	v_max_f32_e32 v1, 0, v1
	v_max_f32_e32 v0, 0, v0
	v_sqrt_f32_e32 v0, v0
	v_sqrt_f32_e32 v1, v1
	s_nop 0
	v_pk_mul_f32 v[0:1], v[2:3], v[0:1]
	s_nop 0
	v_pk_mul_f32 v[30:31], v[14:15], v[0:1]

; #define LAS __attribute__((address_space(3)))
; __global__ void __launch_bounds__(512, 2) fwd_kernel(Args a) {
;     extern __shared__ __attribute__((aligned(16))) unsigned char lds_raw[];
;     LAS unsigned char* lds = (LAS unsigned char*)lds_raw;
;     cg::grid_group grid = cg::this_grid();
;     volatile LAS unsigned* bst = (volatile LAS unsigned*)(lds + 131072 + 64);
;     if (threadIdx.x < 4) bst[threadIdx.x] = 0u;
;     __syncthreads();
;     const XcdBarrier bar = xcd_barrier_post((unsigned*)(a.ws + WS_BAR), bst);
;     typedef const __attribute__((address_space(4))) Args* KArgP;
;     const int pc_lo = a.pc_lo, pc_hi = a.pc_hi;
;     for (int pc = pc_lo; pc < pc_hi; ++pc) {
;         const int op = PROG[pc][0], li = PROG[pc][1], arg = PROG[pc][2], sync = PROG[pc][3];
;         KArgP kap = (KArgP)__builtin_amdgcn_kernarg_segment_ptr();
;         asm volatile("" : "+s"(kap));
;         const Args& a = *(const Args*)kap;
;         const int rep = (op == OP_ATTN) ? arg : 0;
;         switch (op) {
;             case OP_PRO: run_op<OP_PRO>(a, lds, li, arg, rep); break;
;             case OP_NORM: run_op<OP_NORM>(a, lds, li, arg, rep); break;
;             case OP_GQK: run_op<OP_GQK>(a, lds, li, arg, rep); break;
;             case OP_GST: run_op<OP_GST>(a, lds, li, arg, rep); break;
;             case OP_GRES: run_op<OP_GRES>(a, lds, li, arg, rep); break;
;             case OP_ATTN: run_op<OP_ATTN>(a, lds, li, arg, rep); break;
;             case OP_LCONV: run_op<OP_LCONV>(a, lds, li, arg, rep); break;
;             case OP_LRUA: run_op<OP_LRUA>(a, lds, li, arg, rep); break;
;             case OP_LRUC: run_op<OP_LRUC>(a, lds, li, arg, rep); break;
;             default: run_op<OP_GUP>(a, lds, li, arg, rep); break;
;         }
;         if (sync && pc + 1 < pc_hi) { if (pc == 0) grid.sync(); else xcd_barrier(bar); }
;     }
; }
	.amdhsa_kernel _Z10fwd_kernel4Args
		.amdhsa_group_segment_fixed_size 0
		.amdhsa_private_segment_fixed_size 0
		.amdhsa_kernarg_size 488
		.amdhsa_user_sgpr_count 2
		.amdhsa_user_sgpr_dispatch_ptr 0
		.amdhsa_user_sgpr_queue_ptr 0
		.amdhsa_user_sgpr_kernarg_segment_ptr 1
		.amdhsa_user_sgpr_dispatch_id 0
		.amdhsa_user_sgpr_kernarg_preload_length 0
		.amdhsa_user_sgpr_kernarg_preload_offset 0
		.amdhsa_user_sgpr_private_segment_size 0
		.amdhsa_uses_dynamic_stack 0
		.amdhsa_enable_private_segment 0
		.amdhsa_system_sgpr_workgroup_id_x 1
		.amdhsa_system_sgpr_workgroup_id_y 0
		.amdhsa_system_sgpr_workgroup_id_z 0
		.amdhsa_system_sgpr_workgroup_info 0
		.amdhsa_system_vgpr_workitem_id 2
		.amdhsa_next_free_vgpr 256
		.amdhsa_next_free_sgpr 102
		.amdhsa_accum_offset 256
		.amdhsa_reserve_vcc 1
		.amdhsa_float_round_mode_32 0
		.amdhsa_float_round_mode_16_64 0
		.amdhsa_float_denorm_mode_32 3
		.amdhsa_float_denorm_mode_16_64 3
		.amdhsa_dx10_clamp 1
		.amdhsa_ieee_mode 1
		.amdhsa_fp16_overflow 0
		.amdhsa_tg_split 0
		.amdhsa_exception_fp_ieee_invalid_op 0
		.amdhsa_exception_fp_denorm_src 0
		.amdhsa_exception_fp_ieee_div_zero 0
		.amdhsa_exception_fp_ieee_overflow 0
		.amdhsa_exception_fp_ieee_underflow 0
		.amdhsa_exception_fp_ieee_inexact 0
		.amdhsa_exception_int_div_zero 0
	.end_amdhsa_kernel

; #define LAS __attribute__((address_space(3)))
; __global__ void __launch_bounds__(512, 2) fwd_kernel(Args a) {
;     extern __shared__ __attribute__((aligned(16))) unsigned char lds_raw[];
;     LAS unsigned char* lds = (LAS unsigned char*)lds_raw;
;     cg::grid_group grid = cg::this_grid();
;     volatile LAS unsigned* bst = (volatile LAS unsigned*)(lds + 131072 + 64);
;     if (threadIdx.x < 4) bst[threadIdx.x] = 0u;
;     __syncthreads();
;     const XcdBarrier bar = xcd_barrier_post((unsigned*)(a.ws + WS_BAR), bst);
;     typedef const __attribute__((address_space(4))) Args* KArgP;
;     const int pc_lo = a.pc_lo, pc_hi = a.pc_hi;
;     for (int pc = pc_lo; pc < pc_hi; ++pc) {
;         const int op = PROG[pc][0], li = PROG[pc][1], arg = PROG[pc][2], sync = PROG[pc][3];
;         KArgP kap = (KArgP)__builtin_amdgcn_kernarg_segment_ptr();
;         asm volatile("" : "+s"(kap));
;         const Args& a = *(const Args*)kap;
;         const int rep = (op == OP_ATTN) ? arg : 0;
;         switch (op) {
;             case OP_PRO: run_op<OP_PRO>(a, lds, li, arg, rep); break;
;             case OP_NORM: run_op<OP_NORM>(a, lds, li, arg, rep); break;
;             case OP_GQK: run_op<OP_GQK>(a, lds, li, arg, rep); break;
;             case OP_GST: run_op<OP_GST>(a, lds, li, arg, rep); break;
;             case OP_GRES: run_op<OP_GRES>(a, lds, li, arg, rep); break;
;             case OP_ATTN: run_op<OP_ATTN>(a, lds, li, arg, rep); break;
;             case OP_LCONV: run_op<OP_LCONV>(a, lds, li, arg, rep); break;
;             case OP_LRUA: run_op<OP_LRUA>(a, lds, li, arg, rep); break;
;             case OP_LRUC: run_op<OP_LRUC>(a, lds, li, arg, rep); break;
;             default: run_op<OP_GUP>(a, lds, li, arg, rep); break;
;         }
;         if (sync && pc + 1 < pc_hi) { if (pc == 0) grid.sync(); else xcd_barrier(bar); }
;     }
; }
amdhsa.kernels:
  - .agpr_count:     0
    .args:
      - .offset:         0
        .size:           232
        .value_kind:     by_value
      - .offset:         232
        .size:           4
        .value_kind:     hidden_block_count_x
      - .offset:         236
        .size:           4
        .value_kind:     hidden_block_count_y
      - .offset:         240
        .size:           4
        .value_kind:     hidden_block_count_z
      - .offset:         244
        .size:           2
        .value_kind:     hidden_group_size_x
      - .offset:         246
        .size:           2
        .value_kind:     hidden_group_size_y
      - .offset:         248
        .size:           2
        .value_kind:     hidden_group_size_z
      - .offset:         250
        .size:           2
        .value_kind:     hidden_remainder_x
      - .offset:         252
        .size:           2
        .value_kind:     hidden_remainder_y
      - .offset:         254
        .size:           2
        .value_kind:     hidden_remainder_z
      - .offset:         272
        .size:           8
        .value_kind:     hidden_global_offset_x
      - .offset:         280
        .size:           8
        .value_kind:     hidden_global_offset_y
      - .offset:         288
        .size:           8
        .value_kind:     hidden_global_offset_z
      - .offset:         296
        .size:           2
        .value_kind:     hidden_grid_dims
      - .offset:         320
        .size:           8
        .value_kind:     hidden_multigrid_sync_arg
      - .offset:         352
        .size:           4
        .value_kind:     hidden_dynamic_lds_size
    .group_segment_fixed_size: 0
    .kernarg_segment_align: 8
    .kernarg_segment_size: 488
    .language:       OpenCL C
    .language_version:
      - 2
      - 0
    .max_flat_workgroup_size: 512
    .name:           _Z10fwd_kernel4Args
    .private_segment_fixed_size: 0
    .sgpr_count:     108
    .sgpr_spill_count: 142
    .symbol:         _Z10fwd_kernel4Args.kd
    .uniform_work_group_size: 1
    .uses_dynamic_stack: false
    .vgpr_count:     256
    .vgpr_spill_count: 0
    .wavefront_size: 64
